# GEMM K-loops (P1,P4,P5,P6,P7): pointer-select SALU block moved below phase-1 LDS reads and DMA issue
# baseline (speedup 1.0000x reference)
.LBB0_162:
	v_add_u32_e32 v144, s82, v171
	ds_read_b128 v[132:135], v144
	ds_read_b128 v[158:161], v144 offset:1024
	ds_read_b128 v[162:165], v144 offset:2048
	ds_read_b128 v[166:169], v144 offset:3072
	v_add_u32_e32 v144, s83, v171
	ds_read_b128 v[184:187], v144
	ds_read_b128 v[188:191], v144 offset:1024
	ds_read_b128 v[192:195], v144 offset:2048
	ds_read_b128 v[196:199], v144 offset:3072
	v_lshl_add_u64 v[232:233], v[128:129], 0, s[56:57]
	s_add_i32 m0, s29, 0xc000
	ds_read_b128 v[200:203], v181
	ds_read_b128 v[204:207], v181 offset:1024
	ds_read_b128 v[208:211], v181 offset:2048
	ds_read_b128 v[212:215], v181 offset:3072
	ds_read_b128 v[216:219], v181 offset:4096
	ds_read_b128 v[220:223], v181 offset:5120
	ds_read_b128 v[224:227], v181 offset:6144
	ds_read_b128 v[228:231], v181 offset:7168
	global_load_lds_dwordx4 v[232:233], off
	v_lshl_add_u64 v[232:233], v[130:131], 0, s[56:57]
	s_add_i32 m0, s29, 0xe000
	s_nop 0
	global_load_lds_dwordx4 v[232:233], off
	s_cmpk_eq_i32 s56, 0x700
	s_cselect_b64 s[62:63], -1, 0
	s_cmpk_lg_i32 s56, 0x700
	s_cselect_b64 s[60:61], -1, 0
	s_add_u32 s64, s42, s56
	s_addc_u32 s65, s43, s57
	s_and_b64 vcc, exec, s[62:63]
	s_mov_b64 s[58:59], s[48:49]
	s_cbranch_vccnz .Lhzp1_166
	s_add_u32 s58, s64, 0x180
	s_addc_u32 s59, s65, 0
	s_cmp_gt_u32 s92, 12
	s_cbranch_scc0 .Lhzp1_166
	s_add_i32 s10, s92, -13
	s_lshl_b64 s[58:59], s[10:11], 7
	s_add_u32 s58, s86, s58
	s_addc_u32 s59, s87, s59

.Lhzp1_done:
	s_add_u32 s10, s64, 0x100
	s_addc_u32 s95, s65, 0
	s_and_b64 s[64:65], exec, s[62:63]
	s_cselect_b32 s65, s23, s95
	s_cselect_b32 s64, s90, s10
	s_add_u32 s10, s94, 0x100
	s_addc_u32 s93, s93, 0
	s_and_b64 s[62:63], exec, s[62:63]
	s_cselect_b32 s63, s21, s93
	s_cselect_b32 s62, s91, s10
	s_waitcnt vmcnt(8)
	s_waitcnt lgkmcnt(0)
	s_barrier
	s_setprio 1
	s_waitcnt lgkmcnt(0)
	v_mfma_f32_16x16x32_bf16 v[124:127], v[132:135], v[200:203], v[124:127]
	v_mfma_f32_16x16x32_bf16 v[120:123], v[162:165], v[200:203], v[120:123]
	v_mfma_f32_16x16x32_bf16 v[108:111], v[132:135], v[208:211], v[108:111]
	v_mfma_f32_16x16x32_bf16 v[104:107], v[162:165], v[208:211], v[104:107]
	v_mfma_f32_16x16x32_bf16 v[92:95], v[132:135], v[216:219], v[92:95]
	v_mfma_f32_16x16x32_bf16 v[88:91], v[162:165], v[216:219], v[88:91]
	v_mfma_f32_16x16x32_bf16 v[76:79], v[132:135], v[224:227], v[76:79]
	v_mfma_f32_16x16x32_bf16 v[72:75], v[162:165], v[224:227], v[72:75]
	v_mfma_f32_16x16x32_bf16 v[124:127], v[158:161], v[204:207], v[124:127]
	v_mfma_f32_16x16x32_bf16 v[120:123], v[166:169], v[204:207], v[120:123]
	v_mfma_f32_16x16x32_bf16 v[108:111], v[158:161], v[212:215], v[108:111]
	v_mfma_f32_16x16x32_bf16 v[104:107], v[166:169], v[212:215], v[104:107]
	v_mfma_f32_16x16x32_bf16 v[92:95], v[158:161], v[220:223], v[92:95]
	v_mfma_f32_16x16x32_bf16 v[88:91], v[166:169], v[220:223], v[88:91]
	v_mfma_f32_16x16x32_bf16 v[76:79], v[158:161], v[228:231], v[76:79]
	v_mfma_f32_16x16x32_bf16 v[72:75], v[166:169], v[228:231], v[72:75]
	s_setprio 0
	s_setprio 1
	v_mfma_f32_16x16x32_bf16 v[116:119], v[184:187], v[200:203], v[116:119]
	v_mfma_f32_16x16x32_bf16 v[112:115], v[192:195], v[200:203], v[112:115]
	v_mfma_f32_16x16x32_bf16 v[100:103], v[184:187], v[208:211], v[100:103]
	v_mfma_f32_16x16x32_bf16 v[96:99], v[192:195], v[208:211], v[96:99]
	v_mfma_f32_16x16x32_bf16 v[84:87], v[184:187], v[216:219], v[84:87]
	v_mfma_f32_16x16x32_bf16 v[80:83], v[192:195], v[216:219], v[80:83]
	v_mfma_f32_16x16x32_bf16 v[68:71], v[184:187], v[224:227], v[68:71]
	v_mfma_f32_16x16x32_bf16 v[64:67], v[192:195], v[224:227], v[64:67]
	v_mfma_f32_16x16x32_bf16 v[116:119], v[188:191], v[204:207], v[116:119]
	v_mfma_f32_16x16x32_bf16 v[112:115], v[196:199], v[204:207], v[112:115]
	v_mfma_f32_16x16x32_bf16 v[100:103], v[188:191], v[212:215], v[100:103]
	v_mfma_f32_16x16x32_bf16 v[96:99], v[196:199], v[212:215], v[96:99]
	v_mfma_f32_16x16x32_bf16 v[84:87], v[188:191], v[220:223], v[84:87]
	v_mfma_f32_16x16x32_bf16 v[80:83], v[196:199], v[220:223], v[80:83]
	v_mfma_f32_16x16x32_bf16 v[68:71], v[188:191], v[228:231], v[68:71]
	v_mfma_f32_16x16x32_bf16 v[64:67], v[196:199], v[228:231], v[64:67]
	s_setprio 0
	s_barrier
	s_add_i32 s10, s82, s66
	v_lshl_add_u64 v[232:233], s[62:63], 0, v[138:139]
	s_mov_b32 m0, s10
	ds_read_b128 v[200:203], v181 offset:16384
	ds_read_b128 v[204:207], v181 offset:17408
	ds_read_b128 v[208:211], v181 offset:18432
	ds_read_b128 v[212:215], v181 offset:19456
	ds_read_b128 v[216:219], v181 offset:20480
	ds_read_b128 v[220:223], v181 offset:21504
	ds_read_b128 v[224:227], v181 offset:22528
	ds_read_b128 v[228:231], v181 offset:23552
	global_load_lds_dwordx4 v[232:233], off
	s_add_i32 m0, s10, 0x2000
	v_lshl_add_u64 v[232:233], s[62:63], 0, v[142:143]
	s_add_u32 s62, s62, 0x40000
	s_addc_u32 s63, s63, 0
	s_add_i32 s10, s83, s66
	global_load_lds_dwordx4 v[232:233], off
	v_lshl_add_u64 v[232:233], s[62:63], 0, v[138:139]
	s_mov_b32 m0, s10
	s_nop 0
	global_load_lds_dwordx4 v[232:233], off
	v_lshl_add_u64 v[232:233], s[62:63], 0, v[142:143]
	s_add_i32 m0, s10, 0x2000
	s_nop 0
	global_load_lds_dwordx4 v[232:233], off
	v_lshl_add_u64 v[232:233], s[64:65], 0, v[136:137]
	s_mov_b32 m0, s29
	s_nop 0
	global_load_lds_dwordx4 v[232:233], off
	v_lshl_add_u64 v[232:233], s[64:65], 0, v[140:141]
	s_mov_b32 m0, s31
	s_nop 0
	global_load_lds_dwordx4 v[232:233], off
	s_waitcnt vmcnt(8)
	s_waitcnt lgkmcnt(0)
	s_barrier
	s_setprio 1
	s_waitcnt lgkmcnt(0)
	v_mfma_f32_16x16x32_bf16 v[60:63], v[132:135], v[200:203], v[60:63]
	v_mfma_f32_16x16x32_bf16 v[56:59], v[162:165], v[200:203], v[56:59]
	v_mfma_f32_16x16x32_bf16 v[44:47], v[132:135], v[208:211], v[44:47]
	v_mfma_f32_16x16x32_bf16 v[40:43], v[162:165], v[208:211], v[40:43]
	v_mfma_f32_16x16x32_bf16 v[28:31], v[132:135], v[216:219], v[28:31]
	v_mfma_f32_16x16x32_bf16 v[24:27], v[162:165], v[216:219], v[24:27]
	v_mfma_f32_16x16x32_bf16 v[12:15], v[132:135], v[224:227], v[12:15]
	v_mfma_f32_16x16x32_bf16 v[8:11], v[162:165], v[224:227], v[8:11]
	v_mfma_f32_16x16x32_bf16 v[60:63], v[158:161], v[204:207], v[60:63]
	v_mfma_f32_16x16x32_bf16 v[56:59], v[166:169], v[204:207], v[56:59]
	v_mfma_f32_16x16x32_bf16 v[44:47], v[158:161], v[212:215], v[44:47]
	v_mfma_f32_16x16x32_bf16 v[40:43], v[166:169], v[212:215], v[40:43]
	v_mfma_f32_16x16x32_bf16 v[28:31], v[158:161], v[220:223], v[28:31]
	v_mfma_f32_16x16x32_bf16 v[24:27], v[166:169], v[220:223], v[24:27]
	v_mfma_f32_16x16x32_bf16 v[12:15], v[158:161], v[228:231], v[12:15]
	v_mfma_f32_16x16x32_bf16 v[8:11], v[166:169], v[228:231], v[8:11]
	s_setprio 0
	s_setprio 1
	v_mfma_f32_16x16x32_bf16 v[52:55], v[184:187], v[200:203], v[52:55]
	v_mfma_f32_16x16x32_bf16 v[48:51], v[192:195], v[200:203], v[48:51]
	v_mfma_f32_16x16x32_bf16 v[36:39], v[184:187], v[208:211], v[36:39]
	v_mfma_f32_16x16x32_bf16 v[32:35], v[192:195], v[208:211], v[32:35]
	v_mfma_f32_16x16x32_bf16 v[20:23], v[184:187], v[216:219], v[20:23]
	v_mfma_f32_16x16x32_bf16 v[16:19], v[192:195], v[216:219], v[16:19]
	v_mfma_f32_16x16x32_bf16 v[4:7], v[184:187], v[224:227], v[4:7]
	v_mfma_f32_16x16x32_bf16 v[0:3], v[192:195], v[224:227], v[0:3]
	v_mfma_f32_16x16x32_bf16 v[52:55], v[188:191], v[204:207], v[52:55]
	v_mfma_f32_16x16x32_bf16 v[48:51], v[196:199], v[204:207], v[48:51]
	v_mfma_f32_16x16x32_bf16 v[36:39], v[188:191], v[212:215], v[36:39]
	v_mfma_f32_16x16x32_bf16 v[32:35], v[196:199], v[212:215], v[32:35]
	v_mfma_f32_16x16x32_bf16 v[20:23], v[188:191], v[220:223], v[20:23]
	v_mfma_f32_16x16x32_bf16 v[16:19], v[196:199], v[220:223], v[16:19]
	v_mfma_f32_16x16x32_bf16 v[4:7], v[188:191], v[228:231], v[4:7]
	v_mfma_f32_16x16x32_bf16 v[0:3], v[196:199], v[228:231], v[0:3]
	s_setprio 0
	s_barrier
	s_add_i32 s10, 0, 0x18000
	v_add_u32_e32 v144, s10, v171
	s_add_i32 s93, 0, 0x1c000
	ds_read_b128 v[132:135], v144
	ds_read_b128 v[158:161], v144 offset:1024
	ds_read_b128 v[162:165], v144 offset:2048
	ds_read_b128 v[166:169], v144 offset:3072
	v_add_u32_e32 v144, s93, v171
	ds_read_b128 v[184:187], v144
	ds_read_b128 v[188:191], v144 offset:1024
	ds_read_b128 v[192:195], v144 offset:2048
	ds_read_b128 v[196:199], v144 offset:3072
	s_add_u32 s62, s64, 0x40000
	s_addc_u32 s63, s65, 0
	s_mov_b32 m0, s67
	v_lshl_add_u64 v[232:233], s[62:63], 0, v[136:137]
	ds_read_b128 v[200:203], v181 offset:32768
	ds_read_b128 v[204:207], v181 offset:33792
	ds_read_b128 v[208:211], v181 offset:34816
	ds_read_b128 v[212:215], v181 offset:35840
	ds_read_b128 v[216:219], v181 offset:36864
	ds_read_b128 v[220:223], v181 offset:37888
	ds_read_b128 v[224:227], v181 offset:38912
	ds_read_b128 v[228:231], v181 offset:39936
	global_load_lds_dwordx4 v[232:233], off
	v_lshl_add_u64 v[232:233], s[62:63], 0, v[140:141]
	s_mov_b32 m0, s68
	s_nop 0
	global_load_lds_dwordx4 v[232:233], off
	s_waitcnt vmcnt(8)
	s_waitcnt lgkmcnt(0)
	s_barrier
	s_setprio 1
	s_waitcnt lgkmcnt(0)
	v_mfma_f32_16x16x32_bf16 v[124:127], v[132:135], v[200:203], v[124:127]
	v_mfma_f32_16x16x32_bf16 v[120:123], v[162:165], v[200:203], v[120:123]
	v_mfma_f32_16x16x32_bf16 v[108:111], v[132:135], v[208:211], v[108:111]
	v_mfma_f32_16x16x32_bf16 v[104:107], v[162:165], v[208:211], v[104:107]
	v_mfma_f32_16x16x32_bf16 v[92:95], v[132:135], v[216:219], v[92:95]
	v_mfma_f32_16x16x32_bf16 v[88:91], v[162:165], v[216:219], v[88:91]
	v_mfma_f32_16x16x32_bf16 v[76:79], v[132:135], v[224:227], v[76:79]
	v_mfma_f32_16x16x32_bf16 v[72:75], v[162:165], v[224:227], v[72:75]
	v_mfma_f32_16x16x32_bf16 v[124:127], v[158:161], v[204:207], v[124:127]
	v_mfma_f32_16x16x32_bf16 v[120:123], v[166:169], v[204:207], v[120:123]
	v_mfma_f32_16x16x32_bf16 v[108:111], v[158:161], v[212:215], v[108:111]
	v_mfma_f32_16x16x32_bf16 v[104:107], v[166:169], v[212:215], v[104:107]
	v_mfma_f32_16x16x32_bf16 v[92:95], v[158:161], v[220:223], v[92:95]
	v_mfma_f32_16x16x32_bf16 v[88:91], v[166:169], v[220:223], v[88:91]
	v_mfma_f32_16x16x32_bf16 v[76:79], v[158:161], v[228:231], v[76:79]
	v_mfma_f32_16x16x32_bf16 v[72:75], v[166:169], v[228:231], v[72:75]
	s_setprio 0
	s_setprio 1
	v_mfma_f32_16x16x32_bf16 v[116:119], v[184:187], v[200:203], v[116:119]
	v_mfma_f32_16x16x32_bf16 v[112:115], v[192:195], v[200:203], v[112:115]
	v_mfma_f32_16x16x32_bf16 v[100:103], v[184:187], v[208:211], v[100:103]
	v_mfma_f32_16x16x32_bf16 v[96:99], v[192:195], v[208:211], v[96:99]
	v_mfma_f32_16x16x32_bf16 v[84:87], v[184:187], v[216:219], v[84:87]
	v_mfma_f32_16x16x32_bf16 v[80:83], v[192:195], v[216:219], v[80:83]
	v_mfma_f32_16x16x32_bf16 v[68:71], v[184:187], v[224:227], v[68:71]
	v_mfma_f32_16x16x32_bf16 v[64:67], v[192:195], v[224:227], v[64:67]
	v_mfma_f32_16x16x32_bf16 v[116:119], v[188:191], v[204:207], v[116:119]
	v_mfma_f32_16x16x32_bf16 v[112:115], v[196:199], v[204:207], v[112:115]
	v_mfma_f32_16x16x32_bf16 v[100:103], v[188:191], v[212:215], v[100:103]
	v_mfma_f32_16x16x32_bf16 v[96:99], v[196:199], v[212:215], v[96:99]
	v_mfma_f32_16x16x32_bf16 v[84:87], v[188:191], v[220:223], v[84:87]
	v_mfma_f32_16x16x32_bf16 v[80:83], v[196:199], v[220:223], v[80:83]
	v_mfma_f32_16x16x32_bf16 v[68:71], v[188:191], v[228:231], v[68:71]
	v_mfma_f32_16x16x32_bf16 v[64:67], v[196:199], v[228:231], v[64:67]
	s_setprio 0
	s_barrier
	s_add_i32 s10, s10, s66
	v_lshl_add_u64 v[232:233], s[60:61], 0, v[138:139]
	s_mov_b32 m0, s10
	ds_read_b128 v[200:203], v181 offset:49152
	ds_read_b128 v[204:207], v181 offset:50176
	ds_read_b128 v[208:211], v181 offset:51200
	ds_read_b128 v[212:215], v181 offset:52224
	ds_read_b128 v[216:219], v181 offset:53248
	ds_read_b128 v[220:223], v181 offset:54272
	ds_read_b128 v[224:227], v181 offset:55296
	ds_read_b128 v[228:231], v181 offset:56320
	global_load_lds_dwordx4 v[232:233], off
	s_add_i32 m0, s10, 0x2000
	v_lshl_add_u64 v[232:233], s[60:61], 0, v[142:143]
	s_add_u32 s60, s60, 0x40000
	s_addc_u32 s61, s61, 0
	s_add_i32 s10, s93, s66
	global_load_lds_dwordx4 v[232:233], off
	v_lshl_add_u64 v[232:233], s[60:61], 0, v[138:139]
	s_mov_b32 m0, s10
	s_nop 0
	global_load_lds_dwordx4 v[232:233], off
	v_lshl_add_u64 v[232:233], s[60:61], 0, v[142:143]
	s_add_i32 m0, s10, 0x2000
	s_nop 0
	global_load_lds_dwordx4 v[232:233], off
	v_lshl_add_u64 v[232:233], s[58:59], 0, v[136:137]
	s_mov_b32 m0, s73
	s_nop 0
	global_load_lds_dwordx4 v[232:233], off
	v_lshl_add_u64 v[232:233], s[58:59], 0, v[140:141]
	s_mov_b32 m0, s78
	s_nop 0
	global_load_lds_dwordx4 v[232:233], off
	s_waitcnt vmcnt(8)
	s_waitcnt lgkmcnt(0)
	s_barrier
	s_setprio 1
	s_waitcnt lgkmcnt(0)
	v_mfma_f32_16x16x32_bf16 v[60:63], v[132:135], v[200:203], v[60:63]
	v_mfma_f32_16x16x32_bf16 v[56:59], v[162:165], v[200:203], v[56:59]
	v_mfma_f32_16x16x32_bf16 v[44:47], v[132:135], v[208:211], v[44:47]
	v_mfma_f32_16x16x32_bf16 v[40:43], v[162:165], v[208:211], v[40:43]
	v_mfma_f32_16x16x32_bf16 v[28:31], v[132:135], v[216:219], v[28:31]
	v_mfma_f32_16x16x32_bf16 v[24:27], v[162:165], v[216:219], v[24:27]
	v_mfma_f32_16x16x32_bf16 v[12:15], v[132:135], v[224:227], v[12:15]
	v_mfma_f32_16x16x32_bf16 v[8:11], v[162:165], v[224:227], v[8:11]
	v_mfma_f32_16x16x32_bf16 v[60:63], v[158:161], v[204:207], v[60:63]
	v_mfma_f32_16x16x32_bf16 v[56:59], v[166:169], v[204:207], v[56:59]
	v_mfma_f32_16x16x32_bf16 v[44:47], v[158:161], v[212:215], v[44:47]
	v_mfma_f32_16x16x32_bf16 v[40:43], v[166:169], v[212:215], v[40:43]
	v_mfma_f32_16x16x32_bf16 v[28:31], v[158:161], v[220:223], v[28:31]
	v_mfma_f32_16x16x32_bf16 v[24:27], v[166:169], v[220:223], v[24:27]
	v_mfma_f32_16x16x32_bf16 v[12:15], v[158:161], v[228:231], v[12:15]
	v_mfma_f32_16x16x32_bf16 v[8:11], v[166:169], v[228:231], v[8:11]
	s_setprio 0
	s_setprio 1
	v_mfma_f32_16x16x32_bf16 v[52:55], v[184:187], v[200:203], v[52:55]
	v_mfma_f32_16x16x32_bf16 v[48:51], v[192:195], v[200:203], v[48:51]
	v_mfma_f32_16x16x32_bf16 v[36:39], v[184:187], v[208:211], v[36:39]
	v_mfma_f32_16x16x32_bf16 v[32:35], v[192:195], v[208:211], v[32:35]
	v_mfma_f32_16x16x32_bf16 v[20:23], v[184:187], v[216:219], v[20:23]
	v_mfma_f32_16x16x32_bf16 v[16:19], v[192:195], v[216:219], v[16:19]
	v_mfma_f32_16x16x32_bf16 v[4:7], v[184:187], v[224:227], v[4:7]
	v_mfma_f32_16x16x32_bf16 v[0:3], v[192:195], v[224:227], v[0:3]
	v_mfma_f32_16x16x32_bf16 v[52:55], v[188:191], v[204:207], v[52:55]
	v_mfma_f32_16x16x32_bf16 v[48:51], v[196:199], v[204:207], v[48:51]
	v_mfma_f32_16x16x32_bf16 v[36:39], v[188:191], v[212:215], v[36:39]
	v_mfma_f32_16x16x32_bf16 v[32:35], v[196:199], v[212:215], v[32:35]
	v_mfma_f32_16x16x32_bf16 v[20:23], v[188:191], v[220:223], v[20:23]
	v_mfma_f32_16x16x32_bf16 v[16:19], v[196:199], v[220:223], v[16:19]
	v_mfma_f32_16x16x32_bf16 v[4:7], v[188:191], v[228:231], v[4:7]
	v_mfma_f32_16x16x32_bf16 v[0:3], v[196:199], v[228:231], v[0:3]
	s_setprio 0
	s_barrier
	s_add_i32 s10, s92, 2
	s_add_u32 s56, s56, 0x100
	s_addc_u32 s57, s57, 0
	s_cmp_gt_u32 s92, 13
	s_mov_b32 s92, s10
	s_cbranch_scc1 .LBB0_169
.LBB0_163:
	s_branch .LBB0_162
.LBB0_169:
	s_and_b64 vcc, exec, s[14:15]
	s_cbranch_vccnz .LBB0_173
	s_cmp_gt_i32 s30, 1
	s_mov_b64 s[38:39], -1
	s_cbranch_scc1 .LBB0_174

.LBB0_714:
	v_add_u32_e32 v164, s72, v171
	v_add_u32_e32 v168, s73, v171
	ds_read_b128 v[132:135], v164
	ds_read_b128 v[136:139], v164 offset:1024
	ds_read_b128 v[140:143], v164 offset:2048
	ds_read_b128 v[164:167], v164 offset:3072
	ds_read_b128 v[174:177], v168
	ds_read_b128 v[178:181], v168 offset:1024
	ds_read_b128 v[182:185], v168 offset:2048
	ds_read_b128 v[186:189], v168 offset:3072
	v_lshl_add_u64 v[168:169], v[128:129], 0, s[48:49]
	s_add_i32 m0, s59, 0xc000
	ds_read_b128 v[190:193], v172
	ds_read_b128 v[194:197], v172 offset:1024
	ds_read_b128 v[198:201], v172 offset:2048
	ds_read_b128 v[202:205], v172 offset:3072
	ds_read_b128 v[206:209], v172 offset:4096
	ds_read_b128 v[210:213], v172 offset:5120
	ds_read_b128 v[214:217], v172 offset:6144
	ds_read_b128 v[218:221], v172 offset:7168
	global_load_lds_dwordx4 v[168:169], off
	v_lshl_add_u64 v[168:169], v[130:131], 0, s[48:49]
	s_add_i32 m0, s59, 0xe000
	s_nop 0
	global_load_lds_dwordx4 v[168:169], off
	s_cmpk_eq_i32 s48, 0x700
	s_cselect_b64 s[54:55], -1, 0
	s_cmpk_lg_i32 s48, 0x700
	s_cselect_b64 s[52:53], -1, 0
	s_add_u32 s56, s44, s48
	s_addc_u32 s57, s45, s49
	s_and_b64 vcc, exec, s[54:55]
	s_mov_b64 s[50:51], s[36:37]
	s_cbranch_vccnz .Lhzp4_718
	s_add_u32 s50, s56, 0x180
	s_addc_u32 s51, s57, 0
	s_cmp_gt_u32 s82, 12
	s_cbranch_scc0 .Lhzp4_718
	s_add_i32 s10, s82, -13
	s_lshl_b64 s[50:51], s[10:11], 7
	s_add_u32 s50, s19, s50
	s_addc_u32 s51, s29, s51

.Lhzp4_done:
	s_add_u32 s10, s56, 0x100
	s_addc_u32 s85, s57, 0
	s_and_b64 s[56:57], exec, s[54:55]
	s_cselect_b32 s57, s23, s85
	s_cselect_b32 s56, s80, s10
	s_add_u32 s10, s84, 0x100
	s_addc_u32 s83, s83, 0
	s_and_b64 s[54:55], exec, s[54:55]
	s_cselect_b32 s55, s21, s83
	s_cselect_b32 s54, s81, s10
	s_waitcnt vmcnt(8)
	s_waitcnt lgkmcnt(0)
	s_barrier
	s_setprio 1
	s_waitcnt lgkmcnt(0)
	v_mfma_f32_16x16x32_bf16 v[124:127], v[132:135], v[190:193], v[124:127]
	v_mfma_f32_16x16x32_bf16 v[120:123], v[140:143], v[190:193], v[120:123]
	v_mfma_f32_16x16x32_bf16 v[108:111], v[132:135], v[198:201], v[108:111]
	v_mfma_f32_16x16x32_bf16 v[104:107], v[140:143], v[198:201], v[104:107]
	v_mfma_f32_16x16x32_bf16 v[92:95], v[132:135], v[206:209], v[92:95]
	v_mfma_f32_16x16x32_bf16 v[88:91], v[140:143], v[206:209], v[88:91]
	v_mfma_f32_16x16x32_bf16 v[76:79], v[132:135], v[214:217], v[76:79]
	v_mfma_f32_16x16x32_bf16 v[72:75], v[140:143], v[214:217], v[72:75]
	v_mfma_f32_16x16x32_bf16 v[124:127], v[136:139], v[194:197], v[124:127]
	v_mfma_f32_16x16x32_bf16 v[120:123], v[164:167], v[194:197], v[120:123]
	v_mfma_f32_16x16x32_bf16 v[108:111], v[136:139], v[202:205], v[108:111]
	v_mfma_f32_16x16x32_bf16 v[104:107], v[164:167], v[202:205], v[104:107]
	v_mfma_f32_16x16x32_bf16 v[92:95], v[136:139], v[210:213], v[92:95]
	v_mfma_f32_16x16x32_bf16 v[88:91], v[164:167], v[210:213], v[88:91]
	v_mfma_f32_16x16x32_bf16 v[76:79], v[136:139], v[218:221], v[76:79]
	v_mfma_f32_16x16x32_bf16 v[72:75], v[164:167], v[218:221], v[72:75]
	s_setprio 0
	s_setprio 1
	v_mfma_f32_16x16x32_bf16 v[116:119], v[174:177], v[190:193], v[116:119]
	v_mfma_f32_16x16x32_bf16 v[112:115], v[182:185], v[190:193], v[112:115]
	v_mfma_f32_16x16x32_bf16 v[100:103], v[174:177], v[198:201], v[100:103]
	v_mfma_f32_16x16x32_bf16 v[96:99], v[182:185], v[198:201], v[96:99]
	v_mfma_f32_16x16x32_bf16 v[84:87], v[174:177], v[206:209], v[84:87]
	v_mfma_f32_16x16x32_bf16 v[80:83], v[182:185], v[206:209], v[80:83]
	v_mfma_f32_16x16x32_bf16 v[68:71], v[174:177], v[214:217], v[68:71]
	v_mfma_f32_16x16x32_bf16 v[64:67], v[182:185], v[214:217], v[64:67]
	v_mfma_f32_16x16x32_bf16 v[116:119], v[178:181], v[194:197], v[116:119]
	v_mfma_f32_16x16x32_bf16 v[112:115], v[186:189], v[194:197], v[112:115]
	v_mfma_f32_16x16x32_bf16 v[100:103], v[178:181], v[202:205], v[100:103]
	v_mfma_f32_16x16x32_bf16 v[96:99], v[186:189], v[202:205], v[96:99]
	v_mfma_f32_16x16x32_bf16 v[84:87], v[178:181], v[210:213], v[84:87]
	v_mfma_f32_16x16x32_bf16 v[80:83], v[186:189], v[210:213], v[80:83]
	v_mfma_f32_16x16x32_bf16 v[68:71], v[178:181], v[218:221], v[68:71]
	v_mfma_f32_16x16x32_bf16 v[64:67], v[186:189], v[218:221], v[64:67]
	s_setprio 0
	s_barrier
	s_add_i32 s10, s72, s58
	v_lshl_add_u64 v[168:169], s[54:55], 0, v[146:147]
	s_mov_b32 m0, s10
	ds_read_b128 v[190:193], v172 offset:16384
	ds_read_b128 v[194:197], v172 offset:17408
	ds_read_b128 v[198:201], v172 offset:18432
	ds_read_b128 v[202:205], v172 offset:19456
	ds_read_b128 v[206:209], v172 offset:20480
	ds_read_b128 v[210:213], v172 offset:21504
	ds_read_b128 v[214:217], v172 offset:22528
	ds_read_b128 v[218:221], v172 offset:23552
	global_load_lds_dwordx4 v[168:169], off
	s_add_i32 m0, s10, 0x2000
	v_lshl_add_u64 v[168:169], s[54:55], 0, v[150:151]
	s_add_u32 s54, s54, 0x40000
	s_addc_u32 s55, s55, 0
	s_add_i32 s10, s73, s58
	global_load_lds_dwordx4 v[168:169], off
	v_lshl_add_u64 v[168:169], s[54:55], 0, v[146:147]
	s_mov_b32 m0, s10
	s_nop 0
	global_load_lds_dwordx4 v[168:169], off
	v_lshl_add_u64 v[168:169], s[54:55], 0, v[150:151]
	s_add_i32 m0, s10, 0x2000
	s_nop 0
	global_load_lds_dwordx4 v[168:169], off
	v_lshl_add_u64 v[168:169], s[56:57], 0, v[144:145]
	s_mov_b32 m0, s59
	s_nop 0
	global_load_lds_dwordx4 v[168:169], off
	v_lshl_add_u64 v[168:169], s[56:57], 0, v[148:149]
	s_mov_b32 m0, s60
	s_nop 0
	global_load_lds_dwordx4 v[168:169], off
	s_waitcnt vmcnt(8)
	s_waitcnt lgkmcnt(0)
	s_barrier
	s_setprio 1
	s_waitcnt lgkmcnt(0)
	v_mfma_f32_16x16x32_bf16 v[60:63], v[132:135], v[190:193], v[60:63]
	v_mfma_f32_16x16x32_bf16 v[56:59], v[140:143], v[190:193], v[56:59]
	v_mfma_f32_16x16x32_bf16 v[44:47], v[132:135], v[198:201], v[44:47]
	v_mfma_f32_16x16x32_bf16 v[40:43], v[140:143], v[198:201], v[40:43]
	v_mfma_f32_16x16x32_bf16 v[28:31], v[132:135], v[206:209], v[28:31]
	v_mfma_f32_16x16x32_bf16 v[24:27], v[140:143], v[206:209], v[24:27]
	v_mfma_f32_16x16x32_bf16 v[12:15], v[132:135], v[214:217], v[12:15]
	v_mfma_f32_16x16x32_bf16 v[8:11], v[140:143], v[214:217], v[8:11]
	v_mfma_f32_16x16x32_bf16 v[60:63], v[136:139], v[194:197], v[60:63]
	v_mfma_f32_16x16x32_bf16 v[56:59], v[164:167], v[194:197], v[56:59]
	v_mfma_f32_16x16x32_bf16 v[44:47], v[136:139], v[202:205], v[44:47]
	v_mfma_f32_16x16x32_bf16 v[40:43], v[164:167], v[202:205], v[40:43]
	v_mfma_f32_16x16x32_bf16 v[28:31], v[136:139], v[210:213], v[28:31]
	v_mfma_f32_16x16x32_bf16 v[24:27], v[164:167], v[210:213], v[24:27]
	v_mfma_f32_16x16x32_bf16 v[12:15], v[136:139], v[218:221], v[12:15]
	v_mfma_f32_16x16x32_bf16 v[8:11], v[164:167], v[218:221], v[8:11]
	s_setprio 0
	s_setprio 1
	v_mfma_f32_16x16x32_bf16 v[52:55], v[174:177], v[190:193], v[52:55]
	v_mfma_f32_16x16x32_bf16 v[48:51], v[182:185], v[190:193], v[48:51]
	v_mfma_f32_16x16x32_bf16 v[36:39], v[174:177], v[198:201], v[36:39]
	v_mfma_f32_16x16x32_bf16 v[32:35], v[182:185], v[198:201], v[32:35]
	v_mfma_f32_16x16x32_bf16 v[20:23], v[174:177], v[206:209], v[20:23]
	v_mfma_f32_16x16x32_bf16 v[16:19], v[182:185], v[206:209], v[16:19]
	v_mfma_f32_16x16x32_bf16 v[4:7], v[174:177], v[214:217], v[4:7]
	v_mfma_f32_16x16x32_bf16 v[0:3], v[182:185], v[214:217], v[0:3]
	v_mfma_f32_16x16x32_bf16 v[52:55], v[178:181], v[194:197], v[52:55]
	v_mfma_f32_16x16x32_bf16 v[48:51], v[186:189], v[194:197], v[48:51]
	v_mfma_f32_16x16x32_bf16 v[36:39], v[178:181], v[202:205], v[36:39]
	v_mfma_f32_16x16x32_bf16 v[32:35], v[186:189], v[202:205], v[32:35]
	v_mfma_f32_16x16x32_bf16 v[20:23], v[178:181], v[210:213], v[20:23]
	v_mfma_f32_16x16x32_bf16 v[16:19], v[186:189], v[210:213], v[16:19]
	v_mfma_f32_16x16x32_bf16 v[4:7], v[178:181], v[218:221], v[4:7]
	v_mfma_f32_16x16x32_bf16 v[0:3], v[186:189], v[218:221], v[0:3]
	s_setprio 0
	s_barrier
	s_add_i32 s10, 0, 0x18000
	s_add_i32 s83, 0, 0x1c000
	v_add_u32_e32 v164, s10, v171
	v_add_u32_e32 v168, s83, v171
	ds_read_b128 v[132:135], v164
	ds_read_b128 v[136:139], v164 offset:1024
	ds_read_b128 v[140:143], v164 offset:2048
	ds_read_b128 v[164:167], v164 offset:3072
	ds_read_b128 v[174:177], v168
	ds_read_b128 v[178:181], v168 offset:1024
	ds_read_b128 v[182:185], v168 offset:2048
	ds_read_b128 v[186:189], v168 offset:3072
	s_add_u32 s54, s56, 0x40000
	s_addc_u32 s55, s57, 0
	s_mov_b32 m0, s61
	v_lshl_add_u64 v[168:169], s[54:55], 0, v[144:145]
	ds_read_b128 v[190:193], v172 offset:32768
	ds_read_b128 v[194:197], v172 offset:33792
	ds_read_b128 v[198:201], v172 offset:34816
	ds_read_b128 v[202:205], v172 offset:35840
	ds_read_b128 v[206:209], v172 offset:36864
	ds_read_b128 v[210:213], v172 offset:37888
	ds_read_b128 v[214:217], v172 offset:38912
	ds_read_b128 v[218:221], v172 offset:39936
	global_load_lds_dwordx4 v[168:169], off
	v_lshl_add_u64 v[168:169], s[54:55], 0, v[148:149]
	s_mov_b32 m0, s62
	s_nop 0
	global_load_lds_dwordx4 v[168:169], off
	s_waitcnt vmcnt(8)
	s_waitcnt lgkmcnt(0)
	s_barrier
	s_setprio 1
	s_waitcnt lgkmcnt(0)
	v_mfma_f32_16x16x32_bf16 v[124:127], v[132:135], v[190:193], v[124:127]
	v_mfma_f32_16x16x32_bf16 v[120:123], v[140:143], v[190:193], v[120:123]
	v_mfma_f32_16x16x32_bf16 v[108:111], v[132:135], v[198:201], v[108:111]
	v_mfma_f32_16x16x32_bf16 v[104:107], v[140:143], v[198:201], v[104:107]
	v_mfma_f32_16x16x32_bf16 v[92:95], v[132:135], v[206:209], v[92:95]
	v_mfma_f32_16x16x32_bf16 v[88:91], v[140:143], v[206:209], v[88:91]
	v_mfma_f32_16x16x32_bf16 v[76:79], v[132:135], v[214:217], v[76:79]
	v_mfma_f32_16x16x32_bf16 v[72:75], v[140:143], v[214:217], v[72:75]
	v_mfma_f32_16x16x32_bf16 v[124:127], v[136:139], v[194:197], v[124:127]
	v_mfma_f32_16x16x32_bf16 v[120:123], v[164:167], v[194:197], v[120:123]
	v_mfma_f32_16x16x32_bf16 v[108:111], v[136:139], v[202:205], v[108:111]
	v_mfma_f32_16x16x32_bf16 v[104:107], v[164:167], v[202:205], v[104:107]
	v_mfma_f32_16x16x32_bf16 v[92:95], v[136:139], v[210:213], v[92:95]
	v_mfma_f32_16x16x32_bf16 v[88:91], v[164:167], v[210:213], v[88:91]
	v_mfma_f32_16x16x32_bf16 v[76:79], v[136:139], v[218:221], v[76:79]
	v_mfma_f32_16x16x32_bf16 v[72:75], v[164:167], v[218:221], v[72:75]
	s_setprio 0
	s_setprio 1
	v_mfma_f32_16x16x32_bf16 v[116:119], v[174:177], v[190:193], v[116:119]
	v_mfma_f32_16x16x32_bf16 v[112:115], v[182:185], v[190:193], v[112:115]
	v_mfma_f32_16x16x32_bf16 v[100:103], v[174:177], v[198:201], v[100:103]
	v_mfma_f32_16x16x32_bf16 v[96:99], v[182:185], v[198:201], v[96:99]
	v_mfma_f32_16x16x32_bf16 v[84:87], v[174:177], v[206:209], v[84:87]
	v_mfma_f32_16x16x32_bf16 v[80:83], v[182:185], v[206:209], v[80:83]
	v_mfma_f32_16x16x32_bf16 v[68:71], v[174:177], v[214:217], v[68:71]
	v_mfma_f32_16x16x32_bf16 v[64:67], v[182:185], v[214:217], v[64:67]
	v_mfma_f32_16x16x32_bf16 v[116:119], v[178:181], v[194:197], v[116:119]
	v_mfma_f32_16x16x32_bf16 v[112:115], v[186:189], v[194:197], v[112:115]
	v_mfma_f32_16x16x32_bf16 v[100:103], v[178:181], v[202:205], v[100:103]
	v_mfma_f32_16x16x32_bf16 v[96:99], v[186:189], v[202:205], v[96:99]
	v_mfma_f32_16x16x32_bf16 v[84:87], v[178:181], v[210:213], v[84:87]
	v_mfma_f32_16x16x32_bf16 v[80:83], v[186:189], v[210:213], v[80:83]
	v_mfma_f32_16x16x32_bf16 v[68:71], v[178:181], v[218:221], v[68:71]
	v_mfma_f32_16x16x32_bf16 v[64:67], v[186:189], v[218:221], v[64:67]
	s_setprio 0
	s_barrier
	s_add_i32 s10, s10, s58
	v_lshl_add_u64 v[168:169], s[52:53], 0, v[146:147]
	s_mov_b32 m0, s10
	ds_read_b128 v[190:193], v172 offset:49152
	ds_read_b128 v[194:197], v172 offset:50176
	ds_read_b128 v[198:201], v172 offset:51200
	ds_read_b128 v[202:205], v172 offset:52224
	ds_read_b128 v[206:209], v172 offset:53248
	ds_read_b128 v[210:213], v172 offset:54272
	ds_read_b128 v[214:217], v172 offset:55296
	ds_read_b128 v[218:221], v172 offset:56320
	global_load_lds_dwordx4 v[168:169], off
	s_add_i32 m0, s10, 0x2000
	v_lshl_add_u64 v[168:169], s[52:53], 0, v[150:151]
	s_add_u32 s52, s52, 0x40000
	s_addc_u32 s53, s53, 0
	s_add_i32 s10, s83, s58
	global_load_lds_dwordx4 v[168:169], off
	v_lshl_add_u64 v[168:169], s[52:53], 0, v[146:147]
	s_mov_b32 m0, s10
	s_nop 0
	global_load_lds_dwordx4 v[168:169], off
	v_lshl_add_u64 v[168:169], s[52:53], 0, v[150:151]
	s_add_i32 m0, s10, 0x2000
	s_nop 0
	global_load_lds_dwordx4 v[168:169], off
	v_lshl_add_u64 v[168:169], s[50:51], 0, v[144:145]
	s_mov_b32 m0, s68
	s_nop 0
	global_load_lds_dwordx4 v[168:169], off
	v_lshl_add_u64 v[168:169], s[50:51], 0, v[148:149]
	s_mov_b32 m0, s69
	s_nop 0
	global_load_lds_dwordx4 v[168:169], off
	s_waitcnt vmcnt(8)
	s_waitcnt lgkmcnt(0)
	s_barrier
	s_setprio 1
	s_waitcnt lgkmcnt(0)
	v_mfma_f32_16x16x32_bf16 v[60:63], v[132:135], v[190:193], v[60:63]
	v_mfma_f32_16x16x32_bf16 v[56:59], v[140:143], v[190:193], v[56:59]
	v_mfma_f32_16x16x32_bf16 v[44:47], v[132:135], v[198:201], v[44:47]
	v_mfma_f32_16x16x32_bf16 v[40:43], v[140:143], v[198:201], v[40:43]
	v_mfma_f32_16x16x32_bf16 v[28:31], v[132:135], v[206:209], v[28:31]
	v_mfma_f32_16x16x32_bf16 v[24:27], v[140:143], v[206:209], v[24:27]
	v_mfma_f32_16x16x32_bf16 v[12:15], v[132:135], v[214:217], v[12:15]
	v_mfma_f32_16x16x32_bf16 v[8:11], v[140:143], v[214:217], v[8:11]
	v_mfma_f32_16x16x32_bf16 v[60:63], v[136:139], v[194:197], v[60:63]
	v_mfma_f32_16x16x32_bf16 v[56:59], v[164:167], v[194:197], v[56:59]
	v_mfma_f32_16x16x32_bf16 v[44:47], v[136:139], v[202:205], v[44:47]
	v_mfma_f32_16x16x32_bf16 v[40:43], v[164:167], v[202:205], v[40:43]
	v_mfma_f32_16x16x32_bf16 v[28:31], v[136:139], v[210:213], v[28:31]
	v_mfma_f32_16x16x32_bf16 v[24:27], v[164:167], v[210:213], v[24:27]
	v_mfma_f32_16x16x32_bf16 v[12:15], v[136:139], v[218:221], v[12:15]
	v_mfma_f32_16x16x32_bf16 v[8:11], v[164:167], v[218:221], v[8:11]
	s_setprio 0
	s_setprio 1
	v_mfma_f32_16x16x32_bf16 v[52:55], v[174:177], v[190:193], v[52:55]
	v_mfma_f32_16x16x32_bf16 v[48:51], v[182:185], v[190:193], v[48:51]
	v_mfma_f32_16x16x32_bf16 v[36:39], v[174:177], v[198:201], v[36:39]
	v_mfma_f32_16x16x32_bf16 v[32:35], v[182:185], v[198:201], v[32:35]
	v_mfma_f32_16x16x32_bf16 v[20:23], v[174:177], v[206:209], v[20:23]
	v_mfma_f32_16x16x32_bf16 v[16:19], v[182:185], v[206:209], v[16:19]
	v_mfma_f32_16x16x32_bf16 v[4:7], v[174:177], v[214:217], v[4:7]
	v_mfma_f32_16x16x32_bf16 v[0:3], v[182:185], v[214:217], v[0:3]
	v_mfma_f32_16x16x32_bf16 v[52:55], v[178:181], v[194:197], v[52:55]
	v_mfma_f32_16x16x32_bf16 v[48:51], v[186:189], v[194:197], v[48:51]
	v_mfma_f32_16x16x32_bf16 v[36:39], v[178:181], v[202:205], v[36:39]
	v_mfma_f32_16x16x32_bf16 v[32:35], v[186:189], v[202:205], v[32:35]
	v_mfma_f32_16x16x32_bf16 v[20:23], v[178:181], v[210:213], v[20:23]
	v_mfma_f32_16x16x32_bf16 v[16:19], v[186:189], v[210:213], v[16:19]
	v_mfma_f32_16x16x32_bf16 v[4:7], v[178:181], v[218:221], v[4:7]
	v_mfma_f32_16x16x32_bf16 v[0:3], v[186:189], v[218:221], v[0:3]
	s_setprio 0
	s_barrier
	s_add_i32 s10, s82, 2
	s_add_u32 s48, s48, 0x100
	s_addc_u32 s49, s49, 0
	s_cmp_gt_u32 s82, 13
	s_mov_b32 s82, s10
	s_cbranch_scc1 .LBB0_721
.LBB0_715:
	s_branch .LBB0_714
.LBB0_721:
	s_and_b64 vcc, exec, s[16:17]
	s_cbranch_vccz .LBB0_723
	s_barrier

.LBB0_806:
	v_add_u32_e32 v152, s68, v157
	ds_read_b128 v[166:169], v152
	ds_read_b128 v[170:173], v152 offset:1024
	ds_read_b128 v[174:177], v152 offset:2048
	ds_read_b128 v[178:181], v152 offset:3072
	v_add_u32_e32 v152, s69, v157
	ds_read_b128 v[182:185], v152
	ds_read_b128 v[186:189], v152 offset:1024
	ds_read_b128 v[190:193], v152 offset:2048
	ds_read_b128 v[194:197], v152 offset:3072
	v_lshl_add_u64 v[154:155], v[148:149], 0, s[44:45]
	s_add_i32 m0, s57, 0xc000
	ds_read_b128 v[198:201], v161
	ds_read_b128 v[202:205], v161 offset:1024
	ds_read_b128 v[206:209], v161 offset:2048
	ds_read_b128 v[210:213], v161 offset:3072
	ds_read_b128 v[214:217], v161 offset:4096
	ds_read_b128 v[218:221], v161 offset:5120
	ds_read_b128 v[222:225], v161 offset:6144
	ds_read_b128 v[226:229], v161 offset:7168
	global_load_lds_dwordx4 v[154:155], off
	v_lshl_add_u64 v[154:155], v[150:151], 0, s[44:45]
	s_add_i32 m0, s57, 0xe000
	s_nop 0
	global_load_lds_dwordx4 v[154:155], off
	s_cmpk_eq_i32 s44, 0x700
	s_cselect_b64 s[50:51], -1, 0
	s_cmpk_lg_i32 s44, 0x700
	s_cselect_b64 s[48:49], -1, 0
	s_add_u32 s52, s30, s44
	s_addc_u32 s53, s31, s45
	s_and_b64 vcc, exec, s[50:51]
	s_mov_b64 s[46:47], s[36:37]
	s_cbranch_vccnz .Lhzp5_810
	s_add_u32 s46, s52, 0x180
	s_addc_u32 s47, s53, 0
	s_cmp_gt_u32 s81, 12
	s_cbranch_scc0 .Lhzp5_810
	s_add_i32 s8, s81, -13
	s_lshl_b64 s[46:47], s[8:9], 7
	s_add_u32 s46, s27, s46
	s_addc_u32 s47, s72, s47

.Lhzp5_done:
	s_add_u32 s8, s52, 0x100
	s_addc_u32 s84, s53, 0
	s_and_b64 s[52:53], exec, s[50:51]
	s_cselect_b32 s53, s21, s84
	s_cselect_b32 s52, s79, s8
	s_add_u32 s8, s83, 0x100
	s_addc_u32 s82, s82, 0
	s_and_b64 s[50:51], exec, s[50:51]
	s_cselect_b32 s51, s19, s82
	s_cselect_b32 s50, s80, s8
	s_waitcnt vmcnt(8)
	s_waitcnt lgkmcnt(0)
	s_barrier
	s_setprio 1
	s_waitcnt lgkmcnt(0)
	v_mfma_f32_16x16x32_bf16 v[124:127], v[166:169], v[198:201], v[124:127]
	v_mfma_f32_16x16x32_bf16 v[120:123], v[174:177], v[198:201], v[120:123]
	v_mfma_f32_16x16x32_bf16 v[108:111], v[166:169], v[206:209], v[108:111]
	v_mfma_f32_16x16x32_bf16 v[104:107], v[174:177], v[206:209], v[104:107]
	v_mfma_f32_16x16x32_bf16 v[92:95], v[166:169], v[214:217], v[92:95]
	v_mfma_f32_16x16x32_bf16 v[88:91], v[174:177], v[214:217], v[88:91]
	v_mfma_f32_16x16x32_bf16 v[76:79], v[166:169], v[222:225], v[76:79]
	v_mfma_f32_16x16x32_bf16 v[72:75], v[174:177], v[222:225], v[72:75]
	v_mfma_f32_16x16x32_bf16 v[124:127], v[170:173], v[202:205], v[124:127]
	v_mfma_f32_16x16x32_bf16 v[120:123], v[178:181], v[202:205], v[120:123]
	v_mfma_f32_16x16x32_bf16 v[108:111], v[170:173], v[210:213], v[108:111]
	v_mfma_f32_16x16x32_bf16 v[104:107], v[178:181], v[210:213], v[104:107]
	v_mfma_f32_16x16x32_bf16 v[92:95], v[170:173], v[218:221], v[92:95]
	v_mfma_f32_16x16x32_bf16 v[88:91], v[178:181], v[218:221], v[88:91]
	v_mfma_f32_16x16x32_bf16 v[76:79], v[170:173], v[226:229], v[76:79]
	v_mfma_f32_16x16x32_bf16 v[72:75], v[178:181], v[226:229], v[72:75]
	s_setprio 0
	s_setprio 1
	v_mfma_f32_16x16x32_bf16 v[116:119], v[182:185], v[198:201], v[116:119]
	v_mfma_f32_16x16x32_bf16 v[112:115], v[190:193], v[198:201], v[112:115]
	v_mfma_f32_16x16x32_bf16 v[100:103], v[182:185], v[206:209], v[100:103]
	v_mfma_f32_16x16x32_bf16 v[96:99], v[190:193], v[206:209], v[96:99]
	v_mfma_f32_16x16x32_bf16 v[84:87], v[182:185], v[214:217], v[84:87]
	v_mfma_f32_16x16x32_bf16 v[80:83], v[190:193], v[214:217], v[80:83]
	v_mfma_f32_16x16x32_bf16 v[68:71], v[182:185], v[222:225], v[68:71]
	v_mfma_f32_16x16x32_bf16 v[64:67], v[190:193], v[222:225], v[64:67]
	v_mfma_f32_16x16x32_bf16 v[116:119], v[186:189], v[202:205], v[116:119]
	v_mfma_f32_16x16x32_bf16 v[112:115], v[194:197], v[202:205], v[112:115]
	v_mfma_f32_16x16x32_bf16 v[100:103], v[186:189], v[210:213], v[100:103]
	v_mfma_f32_16x16x32_bf16 v[96:99], v[194:197], v[210:213], v[96:99]
	v_mfma_f32_16x16x32_bf16 v[84:87], v[186:189], v[218:221], v[84:87]
	v_mfma_f32_16x16x32_bf16 v[80:83], v[194:197], v[218:221], v[80:83]
	v_mfma_f32_16x16x32_bf16 v[68:71], v[186:189], v[226:229], v[68:71]
	v_mfma_f32_16x16x32_bf16 v[64:67], v[194:197], v[226:229], v[64:67]
	s_setprio 0
	s_barrier
	s_add_i32 s8, s68, s54
	v_lshl_add_u64 v[154:155], s[50:51], 0, v[128:129]
	s_mov_b32 m0, s8
	ds_read_b128 v[198:201], v161 offset:16384
	ds_read_b128 v[202:205], v161 offset:17408
	ds_read_b128 v[206:209], v161 offset:18432
	ds_read_b128 v[210:213], v161 offset:19456
	ds_read_b128 v[214:217], v161 offset:20480
	ds_read_b128 v[218:221], v161 offset:21504
	ds_read_b128 v[222:225], v161 offset:22528
	ds_read_b128 v[226:229], v161 offset:23552
	global_load_lds_dwordx4 v[154:155], off
	s_add_i32 m0, s8, 0x2000
	v_lshl_add_u64 v[154:155], s[50:51], 0, v[130:131]
	s_add_u32 s50, s50, 0x40000
	s_addc_u32 s51, s51, 0
	s_add_i32 s8, s69, s54
	global_load_lds_dwordx4 v[154:155], off
	v_lshl_add_u64 v[154:155], s[50:51], 0, v[128:129]
	s_mov_b32 m0, s8
	s_nop 0
	global_load_lds_dwordx4 v[154:155], off
	v_lshl_add_u64 v[154:155], s[50:51], 0, v[130:131]
	s_add_i32 m0, s8, 0x2000
	s_nop 0
	global_load_lds_dwordx4 v[154:155], off
	v_lshl_add_u64 v[154:155], s[52:53], 0, v[134:135]
	s_mov_b32 m0, s57
	s_nop 0
	global_load_lds_dwordx4 v[154:155], off
	v_lshl_add_u64 v[154:155], s[52:53], 0, v[132:133]
	s_mov_b32 m0, s58
	s_nop 0
	global_load_lds_dwordx4 v[154:155], off
	s_waitcnt vmcnt(8)
	s_waitcnt lgkmcnt(0)
	s_barrier
	s_setprio 1
	s_waitcnt lgkmcnt(0)
	v_mfma_f32_16x16x32_bf16 v[60:63], v[166:169], v[198:201], v[60:63]
	v_mfma_f32_16x16x32_bf16 v[56:59], v[174:177], v[198:201], v[56:59]
	v_mfma_f32_16x16x32_bf16 v[44:47], v[166:169], v[206:209], v[44:47]
	v_mfma_f32_16x16x32_bf16 v[40:43], v[174:177], v[206:209], v[40:43]
	v_mfma_f32_16x16x32_bf16 v[28:31], v[166:169], v[214:217], v[28:31]
	v_mfma_f32_16x16x32_bf16 v[24:27], v[174:177], v[214:217], v[24:27]
	v_mfma_f32_16x16x32_bf16 v[12:15], v[166:169], v[222:225], v[12:15]
	v_mfma_f32_16x16x32_bf16 v[8:11], v[174:177], v[222:225], v[8:11]
	v_mfma_f32_16x16x32_bf16 v[60:63], v[170:173], v[202:205], v[60:63]
	v_mfma_f32_16x16x32_bf16 v[56:59], v[178:181], v[202:205], v[56:59]
	v_mfma_f32_16x16x32_bf16 v[44:47], v[170:173], v[210:213], v[44:47]
	v_mfma_f32_16x16x32_bf16 v[40:43], v[178:181], v[210:213], v[40:43]
	v_mfma_f32_16x16x32_bf16 v[28:31], v[170:173], v[218:221], v[28:31]
	v_mfma_f32_16x16x32_bf16 v[24:27], v[178:181], v[218:221], v[24:27]
	v_mfma_f32_16x16x32_bf16 v[12:15], v[170:173], v[226:229], v[12:15]
	v_mfma_f32_16x16x32_bf16 v[8:11], v[178:181], v[226:229], v[8:11]
	s_setprio 0
	s_setprio 1
	v_mfma_f32_16x16x32_bf16 v[52:55], v[182:185], v[198:201], v[52:55]
	v_mfma_f32_16x16x32_bf16 v[48:51], v[190:193], v[198:201], v[48:51]
	v_mfma_f32_16x16x32_bf16 v[36:39], v[182:185], v[206:209], v[36:39]
	v_mfma_f32_16x16x32_bf16 v[32:35], v[190:193], v[206:209], v[32:35]
	v_mfma_f32_16x16x32_bf16 v[20:23], v[182:185], v[214:217], v[20:23]
	v_mfma_f32_16x16x32_bf16 v[16:19], v[190:193], v[214:217], v[16:19]
	v_mfma_f32_16x16x32_bf16 v[4:7], v[182:185], v[222:225], v[4:7]
	v_mfma_f32_16x16x32_bf16 v[0:3], v[190:193], v[222:225], v[0:3]
	v_mfma_f32_16x16x32_bf16 v[52:55], v[186:189], v[202:205], v[52:55]
	v_mfma_f32_16x16x32_bf16 v[48:51], v[194:197], v[202:205], v[48:51]
	v_mfma_f32_16x16x32_bf16 v[36:39], v[186:189], v[210:213], v[36:39]
	v_mfma_f32_16x16x32_bf16 v[32:35], v[194:197], v[210:213], v[32:35]
	v_mfma_f32_16x16x32_bf16 v[20:23], v[186:189], v[218:221], v[20:23]
	v_mfma_f32_16x16x32_bf16 v[16:19], v[194:197], v[218:221], v[16:19]
	v_mfma_f32_16x16x32_bf16 v[4:7], v[186:189], v[226:229], v[4:7]
	v_mfma_f32_16x16x32_bf16 v[0:3], v[194:197], v[226:229], v[0:3]
	s_setprio 0
	s_barrier
	s_add_i32 s8, 0, 0x18000
	v_add_u32_e32 v152, s8, v157
	s_add_i32 s82, 0, 0x1c000
	ds_read_b128 v[166:169], v152
	ds_read_b128 v[170:173], v152 offset:1024
	ds_read_b128 v[174:177], v152 offset:2048
	ds_read_b128 v[178:181], v152 offset:3072
	v_add_u32_e32 v152, s82, v157
	ds_read_b128 v[182:185], v152
	ds_read_b128 v[186:189], v152 offset:1024
	ds_read_b128 v[190:193], v152 offset:2048
	ds_read_b128 v[194:197], v152 offset:3072
	s_add_u32 s50, s52, 0x40000
	s_addc_u32 s51, s53, 0
	s_mov_b32 m0, s59
	v_lshl_add_u64 v[154:155], s[50:51], 0, v[134:135]
	ds_read_b128 v[198:201], v161 offset:32768
	ds_read_b128 v[202:205], v161 offset:33792
	ds_read_b128 v[206:209], v161 offset:34816
	ds_read_b128 v[210:213], v161 offset:35840
	ds_read_b128 v[214:217], v161 offset:36864
	ds_read_b128 v[218:221], v161 offset:37888
	ds_read_b128 v[222:225], v161 offset:38912
	ds_read_b128 v[226:229], v161 offset:39936
	global_load_lds_dwordx4 v[154:155], off
	v_lshl_add_u64 v[154:155], s[50:51], 0, v[132:133]
	s_mov_b32 m0, s60
	s_nop 0
	global_load_lds_dwordx4 v[154:155], off
	s_waitcnt vmcnt(8)
	s_waitcnt lgkmcnt(0)
	s_barrier
	s_setprio 1
	s_waitcnt lgkmcnt(0)
	v_mfma_f32_16x16x32_bf16 v[124:127], v[166:169], v[198:201], v[124:127]
	v_mfma_f32_16x16x32_bf16 v[120:123], v[174:177], v[198:201], v[120:123]
	v_mfma_f32_16x16x32_bf16 v[108:111], v[166:169], v[206:209], v[108:111]
	v_mfma_f32_16x16x32_bf16 v[104:107], v[174:177], v[206:209], v[104:107]
	v_mfma_f32_16x16x32_bf16 v[92:95], v[166:169], v[214:217], v[92:95]
	v_mfma_f32_16x16x32_bf16 v[88:91], v[174:177], v[214:217], v[88:91]
	v_mfma_f32_16x16x32_bf16 v[76:79], v[166:169], v[222:225], v[76:79]
	v_mfma_f32_16x16x32_bf16 v[72:75], v[174:177], v[222:225], v[72:75]
	v_mfma_f32_16x16x32_bf16 v[124:127], v[170:173], v[202:205], v[124:127]
	v_mfma_f32_16x16x32_bf16 v[120:123], v[178:181], v[202:205], v[120:123]
	v_mfma_f32_16x16x32_bf16 v[108:111], v[170:173], v[210:213], v[108:111]
	v_mfma_f32_16x16x32_bf16 v[104:107], v[178:181], v[210:213], v[104:107]
	v_mfma_f32_16x16x32_bf16 v[92:95], v[170:173], v[218:221], v[92:95]
	v_mfma_f32_16x16x32_bf16 v[88:91], v[178:181], v[218:221], v[88:91]
	v_mfma_f32_16x16x32_bf16 v[76:79], v[170:173], v[226:229], v[76:79]
	v_mfma_f32_16x16x32_bf16 v[72:75], v[178:181], v[226:229], v[72:75]
	s_setprio 0
	s_setprio 1
	v_mfma_f32_16x16x32_bf16 v[116:119], v[182:185], v[198:201], v[116:119]
	v_mfma_f32_16x16x32_bf16 v[112:115], v[190:193], v[198:201], v[112:115]
	v_mfma_f32_16x16x32_bf16 v[100:103], v[182:185], v[206:209], v[100:103]
	v_mfma_f32_16x16x32_bf16 v[96:99], v[190:193], v[206:209], v[96:99]
	v_mfma_f32_16x16x32_bf16 v[84:87], v[182:185], v[214:217], v[84:87]
	v_mfma_f32_16x16x32_bf16 v[80:83], v[190:193], v[214:217], v[80:83]
	v_mfma_f32_16x16x32_bf16 v[68:71], v[182:185], v[222:225], v[68:71]
	v_mfma_f32_16x16x32_bf16 v[64:67], v[190:193], v[222:225], v[64:67]
	v_mfma_f32_16x16x32_bf16 v[116:119], v[186:189], v[202:205], v[116:119]
	v_mfma_f32_16x16x32_bf16 v[112:115], v[194:197], v[202:205], v[112:115]
	v_mfma_f32_16x16x32_bf16 v[100:103], v[186:189], v[210:213], v[100:103]
	v_mfma_f32_16x16x32_bf16 v[96:99], v[194:197], v[210:213], v[96:99]
	v_mfma_f32_16x16x32_bf16 v[84:87], v[186:189], v[218:221], v[84:87]
	v_mfma_f32_16x16x32_bf16 v[80:83], v[194:197], v[218:221], v[80:83]
	v_mfma_f32_16x16x32_bf16 v[68:71], v[186:189], v[226:229], v[68:71]
	v_mfma_f32_16x16x32_bf16 v[64:67], v[194:197], v[226:229], v[64:67]
	s_setprio 0
	s_barrier
	s_add_i32 s8, s8, s54
	v_lshl_add_u64 v[154:155], s[48:49], 0, v[128:129]
	s_mov_b32 m0, s8
	ds_read_b128 v[198:201], v161 offset:49152
	ds_read_b128 v[202:205], v161 offset:50176
	ds_read_b128 v[206:209], v161 offset:51200
	ds_read_b128 v[210:213], v161 offset:52224
	ds_read_b128 v[214:217], v161 offset:53248
	ds_read_b128 v[218:221], v161 offset:54272
	ds_read_b128 v[222:225], v161 offset:55296
	ds_read_b128 v[226:229], v161 offset:56320
	global_load_lds_dwordx4 v[154:155], off
	s_add_i32 m0, s8, 0x2000
	v_lshl_add_u64 v[154:155], s[48:49], 0, v[130:131]
	s_add_u32 s48, s48, 0x40000
	s_addc_u32 s49, s49, 0
	s_add_i32 s8, s82, s54
	global_load_lds_dwordx4 v[154:155], off
	v_lshl_add_u64 v[154:155], s[48:49], 0, v[128:129]
	s_mov_b32 m0, s8
	s_nop 0
	global_load_lds_dwordx4 v[154:155], off
	v_lshl_add_u64 v[154:155], s[48:49], 0, v[130:131]
	s_add_i32 m0, s8, 0x2000
	s_nop 0
	global_load_lds_dwordx4 v[154:155], off
	v_lshl_add_u64 v[154:155], s[46:47], 0, v[134:135]
	s_mov_b32 m0, s65
	s_nop 0
	global_load_lds_dwordx4 v[154:155], off
	v_lshl_add_u64 v[154:155], s[46:47], 0, v[132:133]
	s_mov_b32 m0, s66
	s_nop 0
	global_load_lds_dwordx4 v[154:155], off
	s_waitcnt vmcnt(8)
	s_waitcnt lgkmcnt(0)
	s_barrier
	s_setprio 1
	s_waitcnt lgkmcnt(0)
	v_mfma_f32_16x16x32_bf16 v[60:63], v[166:169], v[198:201], v[60:63]
	v_mfma_f32_16x16x32_bf16 v[56:59], v[174:177], v[198:201], v[56:59]
	v_mfma_f32_16x16x32_bf16 v[44:47], v[166:169], v[206:209], v[44:47]
	v_mfma_f32_16x16x32_bf16 v[40:43], v[174:177], v[206:209], v[40:43]
	v_mfma_f32_16x16x32_bf16 v[28:31], v[166:169], v[214:217], v[28:31]
	v_mfma_f32_16x16x32_bf16 v[24:27], v[174:177], v[214:217], v[24:27]
	v_mfma_f32_16x16x32_bf16 v[12:15], v[166:169], v[222:225], v[12:15]
	v_mfma_f32_16x16x32_bf16 v[8:11], v[174:177], v[222:225], v[8:11]
	v_mfma_f32_16x16x32_bf16 v[60:63], v[170:173], v[202:205], v[60:63]
	v_mfma_f32_16x16x32_bf16 v[56:59], v[178:181], v[202:205], v[56:59]
	v_mfma_f32_16x16x32_bf16 v[44:47], v[170:173], v[210:213], v[44:47]
	v_mfma_f32_16x16x32_bf16 v[40:43], v[178:181], v[210:213], v[40:43]
	v_mfma_f32_16x16x32_bf16 v[28:31], v[170:173], v[218:221], v[28:31]
	v_mfma_f32_16x16x32_bf16 v[24:27], v[178:181], v[218:221], v[24:27]
	v_mfma_f32_16x16x32_bf16 v[12:15], v[170:173], v[226:229], v[12:15]
	v_mfma_f32_16x16x32_bf16 v[8:11], v[178:181], v[226:229], v[8:11]
	s_setprio 0
	s_setprio 1
	v_mfma_f32_16x16x32_bf16 v[52:55], v[182:185], v[198:201], v[52:55]
	v_mfma_f32_16x16x32_bf16 v[48:51], v[190:193], v[198:201], v[48:51]
	v_mfma_f32_16x16x32_bf16 v[36:39], v[182:185], v[206:209], v[36:39]
	v_mfma_f32_16x16x32_bf16 v[32:35], v[190:193], v[206:209], v[32:35]
	v_mfma_f32_16x16x32_bf16 v[20:23], v[182:185], v[214:217], v[20:23]
	v_mfma_f32_16x16x32_bf16 v[16:19], v[190:193], v[214:217], v[16:19]
	v_mfma_f32_16x16x32_bf16 v[4:7], v[182:185], v[222:225], v[4:7]
	v_mfma_f32_16x16x32_bf16 v[0:3], v[190:193], v[222:225], v[0:3]
	v_mfma_f32_16x16x32_bf16 v[52:55], v[186:189], v[202:205], v[52:55]
	v_mfma_f32_16x16x32_bf16 v[48:51], v[194:197], v[202:205], v[48:51]
	v_mfma_f32_16x16x32_bf16 v[36:39], v[186:189], v[210:213], v[36:39]
	v_mfma_f32_16x16x32_bf16 v[32:35], v[194:197], v[210:213], v[32:35]
	v_mfma_f32_16x16x32_bf16 v[20:23], v[186:189], v[218:221], v[20:23]
	v_mfma_f32_16x16x32_bf16 v[16:19], v[194:197], v[218:221], v[16:19]
	v_mfma_f32_16x16x32_bf16 v[4:7], v[186:189], v[226:229], v[4:7]
	v_mfma_f32_16x16x32_bf16 v[0:3], v[194:197], v[226:229], v[0:3]
	s_setprio 0
	s_barrier
	s_add_i32 s8, s81, 2
	s_add_u32 s44, s44, 0x100
	s_addc_u32 s45, s45, 0
	s_cmp_gt_u32 s81, 13
	s_mov_b32 s81, s8
	s_cbranch_scc1 .LBB0_813
.LBB0_807:
	s_branch .LBB0_806
.LBB0_813:
	s_and_b64 vcc, exec, s[14:15]
	s_cbranch_vccz .LBB0_815
	s_barrier

.LBB0_896:
	v_add_u32_e32 v167, s64, v165
	ds_read_b128 v[132:135], v167
	ds_read_b128 v[156:159], v167 offset:1024
	ds_read_b128 v[160:163], v167 offset:2048
	ds_read_b128 v[168:171], v167 offset:3072
	v_add_u32_e32 v167, s65, v165
	ds_read_b128 v[172:175], v167
	ds_read_b128 v[176:179], v167 offset:1024
	ds_read_b128 v[180:183], v167 offset:2048
	ds_read_b128 v[184:187], v167 offset:3072
	v_lshl_add_u64 v[220:221], v[128:129], 0, s[36:37]
	s_add_i32 m0, s51, 0xc000
	ds_read_b128 v[188:191], v166
	ds_read_b128 v[192:195], v166 offset:1024
	ds_read_b128 v[196:199], v166 offset:2048
	ds_read_b128 v[200:203], v166 offset:3072
	ds_read_b128 v[204:207], v166 offset:4096
	ds_read_b128 v[208:211], v166 offset:5120
	ds_read_b128 v[212:215], v166 offset:6144
	ds_read_b128 v[216:219], v166 offset:7168
	global_load_lds_dwordx4 v[220:221], off
	v_lshl_add_u64 v[220:221], v[130:131], 0, s[36:37]
	s_add_i32 m0, s51, 0xe000
	s_nop 0
	global_load_lds_dwordx4 v[220:221], off
	s_cmpk_eq_i32 s36, 0x1500
	s_cselect_b64 s[44:45], -1, 0
	s_cmpk_lg_i32 s36, 0x1500
	s_cselect_b64 s[40:41], -1, 0
	s_add_u32 s46, s26, s36
	s_addc_u32 s47, s27, s37
	s_and_b64 vcc, exec, s[44:45]
	s_mov_b64 s[38:39], s[28:29]
	s_cbranch_vccnz .Lhzp6_900
	s_add_u32 s38, s46, 0x180
	s_addc_u32 s39, s47, 0
	s_cmp_gt_u32 s78, 40
	s_cbranch_scc0 .Lhzp6_900
	s_sub_i32 s8, s78, 41
	s_lshl_b64 s[38:39], s[8:9], 7
	s_add_u32 s38, s70, s38
	s_addc_u32 s39, s71, s39

.Lhzp6_done:
	s_add_u32 s8, s46, 0x100
	s_addc_u32 s81, s47, 0
	s_and_b64 s[46:47], exec, s[44:45]
	s_cselect_b32 s47, s5, s81
	s_cselect_b32 s46, s4, s8
	s_add_u32 s8, s80, 0x100
	s_addc_u32 s79, s79, 0
	s_and_b64 s[44:45], exec, s[44:45]
	s_cselect_b32 s45, s21, s79
	s_cselect_b32 s44, s20, s8
	s_waitcnt vmcnt(8)
	s_waitcnt lgkmcnt(0)
	s_barrier
	s_setprio 1
	s_waitcnt lgkmcnt(0)
	v_mfma_f32_16x16x32_bf16 v[124:127], v[132:135], v[188:191], v[124:127]
	v_mfma_f32_16x16x32_bf16 v[120:123], v[160:163], v[188:191], v[120:123]
	v_mfma_f32_16x16x32_bf16 v[108:111], v[132:135], v[196:199], v[108:111]
	v_mfma_f32_16x16x32_bf16 v[104:107], v[160:163], v[196:199], v[104:107]
	v_mfma_f32_16x16x32_bf16 v[92:95], v[132:135], v[204:207], v[92:95]
	v_mfma_f32_16x16x32_bf16 v[88:91], v[160:163], v[204:207], v[88:91]
	v_mfma_f32_16x16x32_bf16 v[76:79], v[132:135], v[212:215], v[76:79]
	v_mfma_f32_16x16x32_bf16 v[72:75], v[160:163], v[212:215], v[72:75]
	v_mfma_f32_16x16x32_bf16 v[124:127], v[156:159], v[192:195], v[124:127]
	v_mfma_f32_16x16x32_bf16 v[120:123], v[168:171], v[192:195], v[120:123]
	v_mfma_f32_16x16x32_bf16 v[108:111], v[156:159], v[200:203], v[108:111]
	v_mfma_f32_16x16x32_bf16 v[104:107], v[168:171], v[200:203], v[104:107]
	v_mfma_f32_16x16x32_bf16 v[92:95], v[156:159], v[208:211], v[92:95]
	v_mfma_f32_16x16x32_bf16 v[88:91], v[168:171], v[208:211], v[88:91]
	v_mfma_f32_16x16x32_bf16 v[76:79], v[156:159], v[216:219], v[76:79]
	v_mfma_f32_16x16x32_bf16 v[72:75], v[168:171], v[216:219], v[72:75]
	s_setprio 0
	s_setprio 1
	v_mfma_f32_16x16x32_bf16 v[116:119], v[172:175], v[188:191], v[116:119]
	v_mfma_f32_16x16x32_bf16 v[112:115], v[180:183], v[188:191], v[112:115]
	v_mfma_f32_16x16x32_bf16 v[100:103], v[172:175], v[196:199], v[100:103]
	v_mfma_f32_16x16x32_bf16 v[96:99], v[180:183], v[196:199], v[96:99]
	v_mfma_f32_16x16x32_bf16 v[84:87], v[172:175], v[204:207], v[84:87]
	v_mfma_f32_16x16x32_bf16 v[80:83], v[180:183], v[204:207], v[80:83]
	v_mfma_f32_16x16x32_bf16 v[68:71], v[172:175], v[212:215], v[68:71]
	v_mfma_f32_16x16x32_bf16 v[64:67], v[180:183], v[212:215], v[64:67]
	v_mfma_f32_16x16x32_bf16 v[116:119], v[176:179], v[192:195], v[116:119]
	v_mfma_f32_16x16x32_bf16 v[112:115], v[184:187], v[192:195], v[112:115]
	v_mfma_f32_16x16x32_bf16 v[100:103], v[176:179], v[200:203], v[100:103]
	v_mfma_f32_16x16x32_bf16 v[96:99], v[184:187], v[200:203], v[96:99]
	v_mfma_f32_16x16x32_bf16 v[84:87], v[176:179], v[208:211], v[84:87]
	v_mfma_f32_16x16x32_bf16 v[80:83], v[184:187], v[208:211], v[80:83]
	v_mfma_f32_16x16x32_bf16 v[68:71], v[176:179], v[216:219], v[68:71]
	v_mfma_f32_16x16x32_bf16 v[64:67], v[184:187], v[216:219], v[64:67]
	s_setprio 0
	s_barrier
	s_add_i32 s8, s64, s50
	v_lshl_add_u64 v[220:221], s[44:45], 0, v[138:139]
	s_mov_b32 m0, s8
	ds_read_b128 v[188:191], v166 offset:16384
	ds_read_b128 v[192:195], v166 offset:17408
	ds_read_b128 v[196:199], v166 offset:18432
	ds_read_b128 v[200:203], v166 offset:19456
	ds_read_b128 v[204:207], v166 offset:20480
	ds_read_b128 v[208:211], v166 offset:21504
	ds_read_b128 v[212:215], v166 offset:22528
	ds_read_b128 v[216:219], v166 offset:23552
	global_load_lds_dwordx4 v[220:221], off
	s_add_i32 m0, s8, 0x2000
	v_lshl_add_u64 v[220:221], s[44:45], 0, v[142:143]
	s_add_u32 s44, s44, 0xb0000
	s_addc_u32 s45, s45, 0
	s_add_i32 s8, s65, s50
	global_load_lds_dwordx4 v[220:221], off
	v_lshl_add_u64 v[220:221], s[44:45], 0, v[138:139]
	s_mov_b32 m0, s8
	s_nop 0
	global_load_lds_dwordx4 v[220:221], off
	v_lshl_add_u64 v[220:221], s[44:45], 0, v[142:143]
	s_add_i32 m0, s8, 0x2000
	s_nop 0
	global_load_lds_dwordx4 v[220:221], off
	v_lshl_add_u64 v[220:221], s[46:47], 0, v[136:137]
	s_mov_b32 m0, s51
	s_nop 0
	global_load_lds_dwordx4 v[220:221], off
	v_lshl_add_u64 v[220:221], s[46:47], 0, v[140:141]
	s_mov_b32 m0, s52
	s_nop 0
	global_load_lds_dwordx4 v[220:221], off
	s_waitcnt vmcnt(8)
	s_waitcnt lgkmcnt(0)
	s_barrier
	s_setprio 1
	s_waitcnt lgkmcnt(0)
	v_mfma_f32_16x16x32_bf16 v[60:63], v[132:135], v[188:191], v[60:63]
	v_mfma_f32_16x16x32_bf16 v[56:59], v[160:163], v[188:191], v[56:59]
	v_mfma_f32_16x16x32_bf16 v[44:47], v[132:135], v[196:199], v[44:47]
	v_mfma_f32_16x16x32_bf16 v[40:43], v[160:163], v[196:199], v[40:43]
	v_mfma_f32_16x16x32_bf16 v[28:31], v[132:135], v[204:207], v[28:31]
	v_mfma_f32_16x16x32_bf16 v[24:27], v[160:163], v[204:207], v[24:27]
	v_mfma_f32_16x16x32_bf16 v[12:15], v[132:135], v[212:215], v[12:15]
	v_mfma_f32_16x16x32_bf16 v[8:11], v[160:163], v[212:215], v[8:11]
	v_mfma_f32_16x16x32_bf16 v[60:63], v[156:159], v[192:195], v[60:63]
	v_mfma_f32_16x16x32_bf16 v[56:59], v[168:171], v[192:195], v[56:59]
	v_mfma_f32_16x16x32_bf16 v[44:47], v[156:159], v[200:203], v[44:47]
	v_mfma_f32_16x16x32_bf16 v[40:43], v[168:171], v[200:203], v[40:43]
	v_mfma_f32_16x16x32_bf16 v[28:31], v[156:159], v[208:211], v[28:31]
	v_mfma_f32_16x16x32_bf16 v[24:27], v[168:171], v[208:211], v[24:27]
	v_mfma_f32_16x16x32_bf16 v[12:15], v[156:159], v[216:219], v[12:15]
	v_mfma_f32_16x16x32_bf16 v[8:11], v[168:171], v[216:219], v[8:11]
	s_setprio 0
	s_setprio 1
	v_mfma_f32_16x16x32_bf16 v[52:55], v[172:175], v[188:191], v[52:55]
	v_mfma_f32_16x16x32_bf16 v[48:51], v[180:183], v[188:191], v[48:51]
	v_mfma_f32_16x16x32_bf16 v[36:39], v[172:175], v[196:199], v[36:39]
	v_mfma_f32_16x16x32_bf16 v[32:35], v[180:183], v[196:199], v[32:35]
	v_mfma_f32_16x16x32_bf16 v[20:23], v[172:175], v[204:207], v[20:23]
	v_mfma_f32_16x16x32_bf16 v[16:19], v[180:183], v[204:207], v[16:19]
	v_mfma_f32_16x16x32_bf16 v[4:7], v[172:175], v[212:215], v[4:7]
	v_mfma_f32_16x16x32_bf16 v[0:3], v[180:183], v[212:215], v[0:3]
	v_mfma_f32_16x16x32_bf16 v[52:55], v[176:179], v[192:195], v[52:55]
	v_mfma_f32_16x16x32_bf16 v[48:51], v[184:187], v[192:195], v[48:51]
	v_mfma_f32_16x16x32_bf16 v[36:39], v[176:179], v[200:203], v[36:39]
	v_mfma_f32_16x16x32_bf16 v[32:35], v[184:187], v[200:203], v[32:35]
	v_mfma_f32_16x16x32_bf16 v[20:23], v[176:179], v[208:211], v[20:23]
	v_mfma_f32_16x16x32_bf16 v[16:19], v[184:187], v[208:211], v[16:19]
	v_mfma_f32_16x16x32_bf16 v[4:7], v[176:179], v[216:219], v[4:7]
	v_mfma_f32_16x16x32_bf16 v[0:3], v[184:187], v[216:219], v[0:3]
	s_setprio 0
	s_barrier
	s_add_i32 s8, 0, 0x18000
	v_add_u32_e32 v167, s8, v165
	s_add_i32 s79, 0, 0x1c000
	ds_read_b128 v[132:135], v167
	ds_read_b128 v[156:159], v167 offset:1024
	ds_read_b128 v[160:163], v167 offset:2048
	ds_read_b128 v[168:171], v167 offset:3072
	v_add_u32_e32 v167, s79, v165
	ds_read_b128 v[172:175], v167
	ds_read_b128 v[176:179], v167 offset:1024
	ds_read_b128 v[180:183], v167 offset:2048
	ds_read_b128 v[184:187], v167 offset:3072
	s_add_u32 s44, s46, 0xb0000
	s_addc_u32 s45, s47, 0
	s_mov_b32 m0, s53
	v_lshl_add_u64 v[220:221], s[44:45], 0, v[136:137]
	ds_read_b128 v[188:191], v166 offset:32768
	ds_read_b128 v[192:195], v166 offset:33792
	ds_read_b128 v[196:199], v166 offset:34816
	ds_read_b128 v[200:203], v166 offset:35840
	ds_read_b128 v[204:207], v166 offset:36864
	ds_read_b128 v[208:211], v166 offset:37888
	ds_read_b128 v[212:215], v166 offset:38912
	ds_read_b128 v[216:219], v166 offset:39936
	global_load_lds_dwordx4 v[220:221], off
	v_lshl_add_u64 v[220:221], s[44:45], 0, v[140:141]
	s_mov_b32 m0, s54
	s_nop 0
	global_load_lds_dwordx4 v[220:221], off
	s_waitcnt vmcnt(8)
	s_waitcnt lgkmcnt(0)
	s_barrier
	s_setprio 1
	s_waitcnt lgkmcnt(0)
	v_mfma_f32_16x16x32_bf16 v[124:127], v[132:135], v[188:191], v[124:127]
	v_mfma_f32_16x16x32_bf16 v[120:123], v[160:163], v[188:191], v[120:123]
	v_mfma_f32_16x16x32_bf16 v[108:111], v[132:135], v[196:199], v[108:111]
	v_mfma_f32_16x16x32_bf16 v[104:107], v[160:163], v[196:199], v[104:107]
	v_mfma_f32_16x16x32_bf16 v[92:95], v[132:135], v[204:207], v[92:95]
	v_mfma_f32_16x16x32_bf16 v[88:91], v[160:163], v[204:207], v[88:91]
	v_mfma_f32_16x16x32_bf16 v[76:79], v[132:135], v[212:215], v[76:79]
	v_mfma_f32_16x16x32_bf16 v[72:75], v[160:163], v[212:215], v[72:75]
	v_mfma_f32_16x16x32_bf16 v[124:127], v[156:159], v[192:195], v[124:127]
	v_mfma_f32_16x16x32_bf16 v[120:123], v[168:171], v[192:195], v[120:123]
	v_mfma_f32_16x16x32_bf16 v[108:111], v[156:159], v[200:203], v[108:111]
	v_mfma_f32_16x16x32_bf16 v[104:107], v[168:171], v[200:203], v[104:107]
	v_mfma_f32_16x16x32_bf16 v[92:95], v[156:159], v[208:211], v[92:95]
	v_mfma_f32_16x16x32_bf16 v[88:91], v[168:171], v[208:211], v[88:91]
	v_mfma_f32_16x16x32_bf16 v[76:79], v[156:159], v[216:219], v[76:79]
	v_mfma_f32_16x16x32_bf16 v[72:75], v[168:171], v[216:219], v[72:75]
	s_setprio 0
	s_setprio 1
	v_mfma_f32_16x16x32_bf16 v[116:119], v[172:175], v[188:191], v[116:119]
	v_mfma_f32_16x16x32_bf16 v[112:115], v[180:183], v[188:191], v[112:115]
	v_mfma_f32_16x16x32_bf16 v[100:103], v[172:175], v[196:199], v[100:103]
	v_mfma_f32_16x16x32_bf16 v[96:99], v[180:183], v[196:199], v[96:99]
	v_mfma_f32_16x16x32_bf16 v[84:87], v[172:175], v[204:207], v[84:87]
	v_mfma_f32_16x16x32_bf16 v[80:83], v[180:183], v[204:207], v[80:83]
	v_mfma_f32_16x16x32_bf16 v[68:71], v[172:175], v[212:215], v[68:71]
	v_mfma_f32_16x16x32_bf16 v[64:67], v[180:183], v[212:215], v[64:67]
	v_mfma_f32_16x16x32_bf16 v[116:119], v[176:179], v[192:195], v[116:119]
	v_mfma_f32_16x16x32_bf16 v[112:115], v[184:187], v[192:195], v[112:115]
	v_mfma_f32_16x16x32_bf16 v[100:103], v[176:179], v[200:203], v[100:103]
	v_mfma_f32_16x16x32_bf16 v[96:99], v[184:187], v[200:203], v[96:99]
	v_mfma_f32_16x16x32_bf16 v[84:87], v[176:179], v[208:211], v[84:87]
	v_mfma_f32_16x16x32_bf16 v[80:83], v[184:187], v[208:211], v[80:83]
	v_mfma_f32_16x16x32_bf16 v[68:71], v[176:179], v[216:219], v[68:71]
	v_mfma_f32_16x16x32_bf16 v[64:67], v[184:187], v[216:219], v[64:67]
	s_setprio 0
	s_barrier
	s_add_i32 s8, s8, s50
	v_lshl_add_u64 v[220:221], s[40:41], 0, v[138:139]
	s_mov_b32 m0, s8
	ds_read_b128 v[188:191], v166 offset:49152
	ds_read_b128 v[192:195], v166 offset:50176
	ds_read_b128 v[196:199], v166 offset:51200
	ds_read_b128 v[200:203], v166 offset:52224
	ds_read_b128 v[204:207], v166 offset:53248
	ds_read_b128 v[208:211], v166 offset:54272
	ds_read_b128 v[212:215], v166 offset:55296
	ds_read_b128 v[216:219], v166 offset:56320
	global_load_lds_dwordx4 v[220:221], off
	s_add_i32 m0, s8, 0x2000
	v_lshl_add_u64 v[220:221], s[40:41], 0, v[142:143]
	s_add_u32 s40, s40, 0xb0000
	s_addc_u32 s41, s41, 0
	s_add_i32 s8, s79, s50
	global_load_lds_dwordx4 v[220:221], off
	v_lshl_add_u64 v[220:221], s[40:41], 0, v[138:139]
	s_mov_b32 m0, s8
	s_nop 0
	global_load_lds_dwordx4 v[220:221], off
	v_lshl_add_u64 v[220:221], s[40:41], 0, v[142:143]
	s_add_i32 m0, s8, 0x2000
	s_nop 0
	global_load_lds_dwordx4 v[220:221], off
	v_lshl_add_u64 v[220:221], s[38:39], 0, v[136:137]
	s_mov_b32 m0, s60
	s_nop 0
	global_load_lds_dwordx4 v[220:221], off
	v_lshl_add_u64 v[220:221], s[38:39], 0, v[140:141]
	s_mov_b32 m0, s61
	s_nop 0
	global_load_lds_dwordx4 v[220:221], off
	s_waitcnt vmcnt(8)
	s_waitcnt lgkmcnt(0)
	s_barrier
	s_setprio 1
	s_waitcnt lgkmcnt(0)
	v_mfma_f32_16x16x32_bf16 v[60:63], v[132:135], v[188:191], v[60:63]
	v_mfma_f32_16x16x32_bf16 v[56:59], v[160:163], v[188:191], v[56:59]
	v_mfma_f32_16x16x32_bf16 v[44:47], v[132:135], v[196:199], v[44:47]
	v_mfma_f32_16x16x32_bf16 v[40:43], v[160:163], v[196:199], v[40:43]
	v_mfma_f32_16x16x32_bf16 v[28:31], v[132:135], v[204:207], v[28:31]
	v_mfma_f32_16x16x32_bf16 v[24:27], v[160:163], v[204:207], v[24:27]
	v_mfma_f32_16x16x32_bf16 v[12:15], v[132:135], v[212:215], v[12:15]
	v_mfma_f32_16x16x32_bf16 v[8:11], v[160:163], v[212:215], v[8:11]
	v_mfma_f32_16x16x32_bf16 v[60:63], v[156:159], v[192:195], v[60:63]
	v_mfma_f32_16x16x32_bf16 v[56:59], v[168:171], v[192:195], v[56:59]
	v_mfma_f32_16x16x32_bf16 v[44:47], v[156:159], v[200:203], v[44:47]
	v_mfma_f32_16x16x32_bf16 v[40:43], v[168:171], v[200:203], v[40:43]
	v_mfma_f32_16x16x32_bf16 v[28:31], v[156:159], v[208:211], v[28:31]
	v_mfma_f32_16x16x32_bf16 v[24:27], v[168:171], v[208:211], v[24:27]
	v_mfma_f32_16x16x32_bf16 v[12:15], v[156:159], v[216:219], v[12:15]
	v_mfma_f32_16x16x32_bf16 v[8:11], v[168:171], v[216:219], v[8:11]
	s_setprio 0
	s_setprio 1
	v_mfma_f32_16x16x32_bf16 v[52:55], v[172:175], v[188:191], v[52:55]
	v_mfma_f32_16x16x32_bf16 v[48:51], v[180:183], v[188:191], v[48:51]
	v_mfma_f32_16x16x32_bf16 v[36:39], v[172:175], v[196:199], v[36:39]
	v_mfma_f32_16x16x32_bf16 v[32:35], v[180:183], v[196:199], v[32:35]
	v_mfma_f32_16x16x32_bf16 v[20:23], v[172:175], v[204:207], v[20:23]
	v_mfma_f32_16x16x32_bf16 v[16:19], v[180:183], v[204:207], v[16:19]
	v_mfma_f32_16x16x32_bf16 v[4:7], v[172:175], v[212:215], v[4:7]
	v_mfma_f32_16x16x32_bf16 v[0:3], v[180:183], v[212:215], v[0:3]
	v_mfma_f32_16x16x32_bf16 v[52:55], v[176:179], v[192:195], v[52:55]
	v_mfma_f32_16x16x32_bf16 v[48:51], v[184:187], v[192:195], v[48:51]
	v_mfma_f32_16x16x32_bf16 v[36:39], v[176:179], v[200:203], v[36:39]
	v_mfma_f32_16x16x32_bf16 v[32:35], v[184:187], v[200:203], v[32:35]
	v_mfma_f32_16x16x32_bf16 v[20:23], v[176:179], v[208:211], v[20:23]
	v_mfma_f32_16x16x32_bf16 v[16:19], v[184:187], v[208:211], v[16:19]
	v_mfma_f32_16x16x32_bf16 v[4:7], v[176:179], v[216:219], v[4:7]
	v_mfma_f32_16x16x32_bf16 v[0:3], v[184:187], v[216:219], v[0:3]
	s_setprio 0
	s_barrier
	s_add_i32 s8, s78, 2
	s_add_u32 s36, s36, 0x100
	s_addc_u32 s37, s37, 0
	s_cmp_gt_u32 s78, 41
	s_mov_b32 s78, s8
	s_cbranch_scc1 .LBB0_903
.LBB0_897:
	s_branch .LBB0_896
.LBB0_903:
	s_and_b64 vcc, exec, s[14:15]
	s_cbranch_vccz .LBB0_905
	s_barrier

.LBB0_1018:
	v_add_u32_e32 v144, s61, v220
	v_add_u32_e32 v160, s62, v220
	ds_read_b128 v[132:135], v144
	ds_read_b128 v[136:139], v144 offset:1024
	ds_read_b128 v[140:143], v144 offset:2048
	ds_read_b128 v[144:147], v144 offset:3072
	ds_read_b128 v[148:151], v160
	ds_read_b128 v[152:155], v160 offset:1024
	ds_read_b128 v[156:159], v160 offset:2048
	ds_read_b128 v[160:163], v160 offset:3072
	v_lshl_add_u64 v[216:217], v[128:129], 0, s[38:39]
	s_add_i32 m0, s25, 0xc000
	ds_read_b128 v[164:167], v221
	ds_read_b128 v[168:171], v221 offset:1024
	ds_read_b128 v[172:175], v221 offset:2048
	ds_read_b128 v[176:179], v221 offset:3072
	ds_read_b128 v[180:183], v221 offset:4096
	ds_read_b128 v[204:207], v221 offset:5120
	ds_read_b128 v[208:211], v221 offset:6144
	ds_read_b128 v[212:215], v221 offset:7168
	global_load_lds_dwordx4 v[216:217], off
	v_lshl_add_u64 v[216:217], v[130:131], 0, s[38:39]
	s_add_i32 m0, s25, 0xe000
	s_nop 0
	global_load_lds_dwordx4 v[216:217], off
	s_cmpk_eq_i32 s38, 0x700
	s_cselect_b64 s[44:45], -1, 0
	s_cmpk_lg_i32 s38, 0x700
	s_cselect_b64 s[42:43], -1, 0
	s_add_u32 s46, s28, s38
	s_addc_u32 s47, s29, s39
	s_and_b64 vcc, exec, s[44:45]
	s_mov_b64 s[40:41], s[30:31]
	s_cbranch_vccnz .Lhzp7_1022
	s_add_u32 s40, s46, 0x180
	s_addc_u32 s41, s47, 0
	s_cmp_gt_u32 s71, 12
	s_cbranch_scc0 .Lhzp7_1022
	s_add_i32 s10, s71, -13
	s_lshl_b64 s[40:41], s[10:11], 7
	s_add_u32 s40, s65, s40
	s_addc_u32 s41, s66, s41

.Lhzp7_done:
	s_add_u32 s10, s46, 0x100
	s_addc_u32 s76, s47, 0
	s_and_b64 s[46:47], exec, s[44:45]
	s_cselect_b32 s47, s19, s76
	s_cselect_b32 s46, s69, s10
	s_add_u32 s10, s73, 0x100
	s_addc_u32 s72, s72, 0
	s_and_b64 s[44:45], exec, s[44:45]
	s_cselect_b32 s45, s17, s72
	s_cselect_b32 s44, s70, s10
	s_waitcnt vmcnt(8)
	s_waitcnt lgkmcnt(0)
	s_barrier
	s_setprio 1
	s_waitcnt lgkmcnt(0)
	v_mfma_f32_16x16x32_bf16 v[124:127], v[132:135], v[164:167], v[124:127]
	v_mfma_f32_16x16x32_bf16 v[120:123], v[140:143], v[164:167], v[120:123]
	v_mfma_f32_16x16x32_bf16 v[108:111], v[132:135], v[172:175], v[108:111]
	v_mfma_f32_16x16x32_bf16 v[104:107], v[140:143], v[172:175], v[104:107]
	v_mfma_f32_16x16x32_bf16 v[92:95], v[132:135], v[180:183], v[92:95]
	v_mfma_f32_16x16x32_bf16 v[88:91], v[140:143], v[180:183], v[88:91]
	v_mfma_f32_16x16x32_bf16 v[76:79], v[132:135], v[208:211], v[76:79]
	v_mfma_f32_16x16x32_bf16 v[72:75], v[140:143], v[208:211], v[72:75]
	v_mfma_f32_16x16x32_bf16 v[124:127], v[136:139], v[168:171], v[124:127]
	v_mfma_f32_16x16x32_bf16 v[120:123], v[144:147], v[168:171], v[120:123]
	v_mfma_f32_16x16x32_bf16 v[108:111], v[136:139], v[176:179], v[108:111]
	v_mfma_f32_16x16x32_bf16 v[104:107], v[144:147], v[176:179], v[104:107]
	v_mfma_f32_16x16x32_bf16 v[92:95], v[136:139], v[204:207], v[92:95]
	v_mfma_f32_16x16x32_bf16 v[88:91], v[144:147], v[204:207], v[88:91]
	v_mfma_f32_16x16x32_bf16 v[76:79], v[136:139], v[212:215], v[76:79]
	v_mfma_f32_16x16x32_bf16 v[72:75], v[144:147], v[212:215], v[72:75]
	s_setprio 0
	s_setprio 1
	v_mfma_f32_16x16x32_bf16 v[116:119], v[148:151], v[164:167], v[116:119]
	v_mfma_f32_16x16x32_bf16 v[112:115], v[156:159], v[164:167], v[112:115]
	v_mfma_f32_16x16x32_bf16 v[100:103], v[148:151], v[172:175], v[100:103]
	v_mfma_f32_16x16x32_bf16 v[96:99], v[156:159], v[172:175], v[96:99]
	v_mfma_f32_16x16x32_bf16 v[84:87], v[148:151], v[180:183], v[84:87]
	v_mfma_f32_16x16x32_bf16 v[80:83], v[156:159], v[180:183], v[80:83]
	v_mfma_f32_16x16x32_bf16 v[68:71], v[148:151], v[208:211], v[68:71]
	v_mfma_f32_16x16x32_bf16 v[64:67], v[156:159], v[208:211], v[64:67]
	v_mfma_f32_16x16x32_bf16 v[116:119], v[152:155], v[168:171], v[116:119]
	v_mfma_f32_16x16x32_bf16 v[112:115], v[160:163], v[168:171], v[112:115]
	v_mfma_f32_16x16x32_bf16 v[100:103], v[152:155], v[176:179], v[100:103]
	v_mfma_f32_16x16x32_bf16 v[96:99], v[160:163], v[176:179], v[96:99]
	v_mfma_f32_16x16x32_bf16 v[84:87], v[152:155], v[204:207], v[84:87]
	v_mfma_f32_16x16x32_bf16 v[80:83], v[160:163], v[204:207], v[80:83]
	v_mfma_f32_16x16x32_bf16 v[68:71], v[152:155], v[212:215], v[68:71]
	v_mfma_f32_16x16x32_bf16 v[64:67], v[160:163], v[212:215], v[64:67]
	s_setprio 0
	s_barrier
	s_add_i32 s10, s61, s50
	v_lshl_add_u64 v[216:217], s[44:45], 0, v[186:187]
	s_mov_b32 m0, s10
	ds_read_b128 v[164:167], v221 offset:16384
	ds_read_b128 v[168:171], v221 offset:17408
	ds_read_b128 v[172:175], v221 offset:18432
	ds_read_b128 v[176:179], v221 offset:19456
	ds_read_b128 v[180:183], v221 offset:20480
	ds_read_b128 v[204:207], v221 offset:21504
	ds_read_b128 v[208:211], v221 offset:22528
	ds_read_b128 v[212:215], v221 offset:23552
	global_load_lds_dwordx4 v[216:217], off
	s_add_i32 m0, s10, 0x2000
	v_lshl_add_u64 v[216:217], s[44:45], 0, v[190:191]
	s_add_u32 s44, s44, 0x40000
	s_addc_u32 s45, s45, 0
	s_add_i32 s10, s62, s50
	global_load_lds_dwordx4 v[216:217], off
	v_lshl_add_u64 v[216:217], s[44:45], 0, v[186:187]
	s_mov_b32 m0, s10
	s_nop 0
	global_load_lds_dwordx4 v[216:217], off
	v_lshl_add_u64 v[216:217], s[44:45], 0, v[190:191]
	s_add_i32 m0, s10, 0x2000
	s_nop 0
	global_load_lds_dwordx4 v[216:217], off
	v_lshl_add_u64 v[216:217], s[46:47], 0, v[184:185]
	s_mov_b32 m0, s25
	s_nop 0
	global_load_lds_dwordx4 v[216:217], off
	v_lshl_add_u64 v[216:217], s[46:47], 0, v[188:189]
	s_mov_b32 m0, s51
	s_nop 0
	global_load_lds_dwordx4 v[216:217], off
	s_waitcnt vmcnt(8)
	s_waitcnt lgkmcnt(0)
	s_barrier
	s_setprio 1
	s_waitcnt lgkmcnt(0)
	v_mfma_f32_16x16x32_bf16 v[60:63], v[132:135], v[164:167], v[60:63]
	v_mfma_f32_16x16x32_bf16 v[56:59], v[140:143], v[164:167], v[56:59]
	v_mfma_f32_16x16x32_bf16 v[44:47], v[132:135], v[172:175], v[44:47]
	v_mfma_f32_16x16x32_bf16 v[40:43], v[140:143], v[172:175], v[40:43]
	v_mfma_f32_16x16x32_bf16 v[28:31], v[132:135], v[180:183], v[28:31]
	v_mfma_f32_16x16x32_bf16 v[24:27], v[140:143], v[180:183], v[24:27]
	v_mfma_f32_16x16x32_bf16 v[12:15], v[132:135], v[208:211], v[12:15]
	v_mfma_f32_16x16x32_bf16 v[8:11], v[140:143], v[208:211], v[8:11]
	v_mfma_f32_16x16x32_bf16 v[60:63], v[136:139], v[168:171], v[60:63]
	v_mfma_f32_16x16x32_bf16 v[56:59], v[144:147], v[168:171], v[56:59]
	v_mfma_f32_16x16x32_bf16 v[44:47], v[136:139], v[176:179], v[44:47]
	v_mfma_f32_16x16x32_bf16 v[40:43], v[144:147], v[176:179], v[40:43]
	v_mfma_f32_16x16x32_bf16 v[28:31], v[136:139], v[204:207], v[28:31]
	v_mfma_f32_16x16x32_bf16 v[24:27], v[144:147], v[204:207], v[24:27]
	v_mfma_f32_16x16x32_bf16 v[12:15], v[136:139], v[212:215], v[12:15]
	v_mfma_f32_16x16x32_bf16 v[8:11], v[144:147], v[212:215], v[8:11]
	s_setprio 0
	s_setprio 1
	v_mfma_f32_16x16x32_bf16 v[52:55], v[148:151], v[164:167], v[52:55]
	v_mfma_f32_16x16x32_bf16 v[48:51], v[156:159], v[164:167], v[48:51]
	v_mfma_f32_16x16x32_bf16 v[36:39], v[148:151], v[172:175], v[36:39]
	v_mfma_f32_16x16x32_bf16 v[32:35], v[156:159], v[172:175], v[32:35]
	v_mfma_f32_16x16x32_bf16 v[20:23], v[148:151], v[180:183], v[20:23]
	v_mfma_f32_16x16x32_bf16 v[16:19], v[156:159], v[180:183], v[16:19]
	v_mfma_f32_16x16x32_bf16 v[4:7], v[148:151], v[208:211], v[4:7]
	v_mfma_f32_16x16x32_bf16 v[0:3], v[156:159], v[208:211], v[0:3]
	v_mfma_f32_16x16x32_bf16 v[52:55], v[152:155], v[168:171], v[52:55]
	v_mfma_f32_16x16x32_bf16 v[48:51], v[160:163], v[168:171], v[48:51]
	v_mfma_f32_16x16x32_bf16 v[36:39], v[152:155], v[176:179], v[36:39]
	v_mfma_f32_16x16x32_bf16 v[32:35], v[160:163], v[176:179], v[32:35]
	v_mfma_f32_16x16x32_bf16 v[20:23], v[152:155], v[204:207], v[20:23]
	v_mfma_f32_16x16x32_bf16 v[16:19], v[160:163], v[204:207], v[16:19]
	v_mfma_f32_16x16x32_bf16 v[4:7], v[152:155], v[212:215], v[4:7]
	v_mfma_f32_16x16x32_bf16 v[0:3], v[160:163], v[212:215], v[0:3]
	s_setprio 0
	s_barrier
	s_add_i32 s10, 0, 0x18000
	s_add_i32 s72, 0, 0x1c000
	v_add_u32_e32 v144, s10, v220
	v_add_u32_e32 v160, s72, v220
	ds_read_b128 v[132:135], v144
	ds_read_b128 v[136:139], v144 offset:1024
	ds_read_b128 v[140:143], v144 offset:2048
	ds_read_b128 v[144:147], v144 offset:3072
	ds_read_b128 v[148:151], v160
	ds_read_b128 v[152:155], v160 offset:1024
	ds_read_b128 v[156:159], v160 offset:2048
	ds_read_b128 v[160:163], v160 offset:3072
	s_add_u32 s44, s46, 0x40000
	s_addc_u32 s45, s47, 0
	s_mov_b32 m0, s52
	v_lshl_add_u64 v[216:217], s[44:45], 0, v[184:185]
	ds_read_b128 v[164:167], v221 offset:32768
	ds_read_b128 v[168:171], v221 offset:33792
	ds_read_b128 v[172:175], v221 offset:34816
	ds_read_b128 v[176:179], v221 offset:35840
	ds_read_b128 v[180:183], v221 offset:36864
	ds_read_b128 v[204:207], v221 offset:37888
	ds_read_b128 v[208:211], v221 offset:38912
	ds_read_b128 v[212:215], v221 offset:39936
	global_load_lds_dwordx4 v[216:217], off
	v_lshl_add_u64 v[216:217], s[44:45], 0, v[188:189]
	s_mov_b32 m0, s53
	s_nop 0
	global_load_lds_dwordx4 v[216:217], off
	s_waitcnt vmcnt(8)
	s_waitcnt lgkmcnt(0)
	s_barrier
	s_setprio 1
	s_waitcnt lgkmcnt(0)
	v_mfma_f32_16x16x32_bf16 v[124:127], v[132:135], v[164:167], v[124:127]
	v_mfma_f32_16x16x32_bf16 v[120:123], v[140:143], v[164:167], v[120:123]
	v_mfma_f32_16x16x32_bf16 v[108:111], v[132:135], v[172:175], v[108:111]
	v_mfma_f32_16x16x32_bf16 v[104:107], v[140:143], v[172:175], v[104:107]
	v_mfma_f32_16x16x32_bf16 v[92:95], v[132:135], v[180:183], v[92:95]
	v_mfma_f32_16x16x32_bf16 v[88:91], v[140:143], v[180:183], v[88:91]
	v_mfma_f32_16x16x32_bf16 v[76:79], v[132:135], v[208:211], v[76:79]
	v_mfma_f32_16x16x32_bf16 v[72:75], v[140:143], v[208:211], v[72:75]
	v_mfma_f32_16x16x32_bf16 v[124:127], v[136:139], v[168:171], v[124:127]
	v_mfma_f32_16x16x32_bf16 v[120:123], v[144:147], v[168:171], v[120:123]
	v_mfma_f32_16x16x32_bf16 v[108:111], v[136:139], v[176:179], v[108:111]
	v_mfma_f32_16x16x32_bf16 v[104:107], v[144:147], v[176:179], v[104:107]
	v_mfma_f32_16x16x32_bf16 v[92:95], v[136:139], v[204:207], v[92:95]
	v_mfma_f32_16x16x32_bf16 v[88:91], v[144:147], v[204:207], v[88:91]
	v_mfma_f32_16x16x32_bf16 v[76:79], v[136:139], v[212:215], v[76:79]
	v_mfma_f32_16x16x32_bf16 v[72:75], v[144:147], v[212:215], v[72:75]
	s_setprio 0
	s_setprio 1
	v_mfma_f32_16x16x32_bf16 v[116:119], v[148:151], v[164:167], v[116:119]
	v_mfma_f32_16x16x32_bf16 v[112:115], v[156:159], v[164:167], v[112:115]
	v_mfma_f32_16x16x32_bf16 v[100:103], v[148:151], v[172:175], v[100:103]
	v_mfma_f32_16x16x32_bf16 v[96:99], v[156:159], v[172:175], v[96:99]
	v_mfma_f32_16x16x32_bf16 v[84:87], v[148:151], v[180:183], v[84:87]
	v_mfma_f32_16x16x32_bf16 v[80:83], v[156:159], v[180:183], v[80:83]
	v_mfma_f32_16x16x32_bf16 v[68:71], v[148:151], v[208:211], v[68:71]
	v_mfma_f32_16x16x32_bf16 v[64:67], v[156:159], v[208:211], v[64:67]
	v_mfma_f32_16x16x32_bf16 v[116:119], v[152:155], v[168:171], v[116:119]
	v_mfma_f32_16x16x32_bf16 v[112:115], v[160:163], v[168:171], v[112:115]
	v_mfma_f32_16x16x32_bf16 v[100:103], v[152:155], v[176:179], v[100:103]
	v_mfma_f32_16x16x32_bf16 v[96:99], v[160:163], v[176:179], v[96:99]
	v_mfma_f32_16x16x32_bf16 v[84:87], v[152:155], v[204:207], v[84:87]
	v_mfma_f32_16x16x32_bf16 v[80:83], v[160:163], v[204:207], v[80:83]
	v_mfma_f32_16x16x32_bf16 v[68:71], v[152:155], v[212:215], v[68:71]
	v_mfma_f32_16x16x32_bf16 v[64:67], v[160:163], v[212:215], v[64:67]
	s_setprio 0
	s_barrier
	s_add_i32 s10, s10, s50
	v_lshl_add_u64 v[216:217], s[42:43], 0, v[186:187]
	s_mov_b32 m0, s10
	ds_read_b128 v[164:167], v221 offset:49152
	ds_read_b128 v[168:171], v221 offset:50176
	ds_read_b128 v[172:175], v221 offset:51200
	ds_read_b128 v[176:179], v221 offset:52224
	ds_read_b128 v[180:183], v221 offset:53248
	ds_read_b128 v[204:207], v221 offset:54272
	ds_read_b128 v[208:211], v221 offset:55296
	ds_read_b128 v[212:215], v221 offset:56320
	global_load_lds_dwordx4 v[216:217], off
	s_add_i32 m0, s10, 0x2000
	v_lshl_add_u64 v[216:217], s[42:43], 0, v[190:191]
	s_add_u32 s42, s42, 0x40000
	s_addc_u32 s43, s43, 0
	s_add_i32 s10, s72, s50
	global_load_lds_dwordx4 v[216:217], off
	v_lshl_add_u64 v[216:217], s[42:43], 0, v[186:187]
	s_mov_b32 m0, s10
	s_nop 0
	global_load_lds_dwordx4 v[216:217], off
	v_lshl_add_u64 v[216:217], s[42:43], 0, v[190:191]
	s_add_i32 m0, s10, 0x2000
	s_nop 0
	global_load_lds_dwordx4 v[216:217], off
	v_lshl_add_u64 v[216:217], s[40:41], 0, v[184:185]
	s_mov_b32 m0, s58
	s_nop 0
	global_load_lds_dwordx4 v[216:217], off
	v_lshl_add_u64 v[216:217], s[40:41], 0, v[188:189]
	s_mov_b32 m0, s59
	s_nop 0
	global_load_lds_dwordx4 v[216:217], off
	s_waitcnt vmcnt(8)
	s_waitcnt lgkmcnt(0)
	s_barrier
	s_setprio 1
	s_waitcnt lgkmcnt(0)
	v_mfma_f32_16x16x32_bf16 v[60:63], v[132:135], v[164:167], v[60:63]
	v_mfma_f32_16x16x32_bf16 v[56:59], v[140:143], v[164:167], v[56:59]
	v_mfma_f32_16x16x32_bf16 v[44:47], v[132:135], v[172:175], v[44:47]
	v_mfma_f32_16x16x32_bf16 v[40:43], v[140:143], v[172:175], v[40:43]
	v_mfma_f32_16x16x32_bf16 v[28:31], v[132:135], v[180:183], v[28:31]
	v_mfma_f32_16x16x32_bf16 v[24:27], v[140:143], v[180:183], v[24:27]
	v_mfma_f32_16x16x32_bf16 v[12:15], v[132:135], v[208:211], v[12:15]
	v_mfma_f32_16x16x32_bf16 v[8:11], v[140:143], v[208:211], v[8:11]
	v_mfma_f32_16x16x32_bf16 v[60:63], v[136:139], v[168:171], v[60:63]
	v_mfma_f32_16x16x32_bf16 v[56:59], v[144:147], v[168:171], v[56:59]
	v_mfma_f32_16x16x32_bf16 v[44:47], v[136:139], v[176:179], v[44:47]
	v_mfma_f32_16x16x32_bf16 v[40:43], v[144:147], v[176:179], v[40:43]
	v_mfma_f32_16x16x32_bf16 v[28:31], v[136:139], v[204:207], v[28:31]
	v_mfma_f32_16x16x32_bf16 v[24:27], v[144:147], v[204:207], v[24:27]
	v_mfma_f32_16x16x32_bf16 v[12:15], v[136:139], v[212:215], v[12:15]
	v_mfma_f32_16x16x32_bf16 v[8:11], v[144:147], v[212:215], v[8:11]
	s_setprio 0
	s_setprio 1
	v_mfma_f32_16x16x32_bf16 v[52:55], v[148:151], v[164:167], v[52:55]
	v_mfma_f32_16x16x32_bf16 v[48:51], v[156:159], v[164:167], v[48:51]
	v_mfma_f32_16x16x32_bf16 v[36:39], v[148:151], v[172:175], v[36:39]
	v_mfma_f32_16x16x32_bf16 v[32:35], v[156:159], v[172:175], v[32:35]
	v_mfma_f32_16x16x32_bf16 v[20:23], v[148:151], v[180:183], v[20:23]
	v_mfma_f32_16x16x32_bf16 v[16:19], v[156:159], v[180:183], v[16:19]
	v_mfma_f32_16x16x32_bf16 v[4:7], v[148:151], v[208:211], v[4:7]
	v_mfma_f32_16x16x32_bf16 v[0:3], v[156:159], v[208:211], v[0:3]
	v_mfma_f32_16x16x32_bf16 v[52:55], v[152:155], v[168:171], v[52:55]
	v_mfma_f32_16x16x32_bf16 v[48:51], v[160:163], v[168:171], v[48:51]
	v_mfma_f32_16x16x32_bf16 v[36:39], v[152:155], v[176:179], v[36:39]
	v_mfma_f32_16x16x32_bf16 v[32:35], v[160:163], v[176:179], v[32:35]
	v_mfma_f32_16x16x32_bf16 v[20:23], v[152:155], v[204:207], v[20:23]
	v_mfma_f32_16x16x32_bf16 v[16:19], v[160:163], v[204:207], v[16:19]
	v_mfma_f32_16x16x32_bf16 v[4:7], v[152:155], v[212:215], v[4:7]
	v_mfma_f32_16x16x32_bf16 v[0:3], v[160:163], v[212:215], v[0:3]
	s_setprio 0
	s_barrier
	s_add_i32 s10, s71, 2
	s_add_u32 s38, s38, 0x100
	s_addc_u32 s39, s39, 0
	s_cmp_gt_u32 s71, 13
	s_mov_b32 s71, s10
	s_cbranch_scc1 .LBB0_1025
.LBB0_1019:
	s_branch .LBB0_1018
.LBB0_1025:
	s_and_b64 vcc, exec, s[14:15]
	s_cbranch_vccz .LBB0_1027
	s_barrier
